# step8 + the three late LayerNorm-stat loads of both MLP-up epilogues hoisted into the first load batch (one wait removed per output tile)
# speedup vs baseline: 1.0001x; 1.0001x over previous
.LBB0_775:
	v_lshl_add_u32 v202, s79, 8, v175
	v_ashrrev_i32_e32 v203, 31, v202
	v_lshl_add_u64 v[128:129], v[202:203], 3, s[20:21]
	global_load_dwordx2 v[128:129], v[128:129], off
	v_or_b32_e32 v200, 16, v202
	v_or_b32_e32 v198, 32, v202
	v_ashrrev_i32_e32 v201, 31, v200
	v_ashrrev_i32_e32 v199, 31, v198
	v_lshl_add_u64 v[130:131], v[200:201], 3, s[20:21]
	v_lshl_add_u64 v[132:133], v[198:199], 3, s[20:21]
	global_load_dwordx2 v[130:131], v[130:131], off
	s_nop 0
	global_load_dwordx2 v[132:133], v[132:133], off
	v_or_b32_e32 v196, 48, v202
	v_add_u32_e32 v194, 0x80, v202
	v_ashrrev_i32_e32 v197, 31, v196
	v_ashrrev_i32_e32 v195, 31, v194
	v_lshl_add_u64 v[134:135], v[196:197], 3, s[20:21]
	v_lshl_add_u64 v[136:137], v[194:195], 3, s[20:21]
	global_load_dwordx2 v[134:135], v[134:135], off
	s_nop 0
	global_load_dwordx2 v[136:137], v[136:137], off
	v_add_u32_e32 v192, 0x90, v202
	v_ashrrev_i32_e32 v193, 31, v192
	v_add_u32_e32 v206, 0xa0, v202
	v_ashrrev_i32_e32 v207, 31, v206
	v_add_u32_e32 v204, 0xb0, v202
	v_ashrrev_i32_e32 v205, 31, v204
	v_lshl_or_b32 v208, s78, 8, v181
	v_ashrrev_i32_e32 v209, 31, v208
	v_lshl_add_u64 v[248:249], v[192:193], 3, s[20:21]
	global_load_dwordx2 v[248:249], v[248:249], off
	v_lshl_add_u64 v[246:247], v[206:207], 3, s[20:21]
	global_load_dwordx2 v[246:247], v[246:247], off
	v_lshl_add_u64 v[244:245], v[204:205], 3, s[20:21]
	global_load_dwordx2 v[244:245], v[244:245], off
	s_waitcnt vmcnt(0)
	v_pk_mul_f32 v[166:167], v[128:129], s[36:37] op_sel_hi:[1,0]
	s_nop 0
	v_fma_f32 v128, -v166, v166, v167
	v_max_f32_e32 v128, 0, v128
	v_add_f32_e32 v128, 0x3727c5ac, v128
	v_cmp_gt_f32_e32 vcc, s63, v128
	v_pk_mul_f32 v[162:163], v[130:131], s[36:37] op_sel_hi:[1,0]
	v_pk_mul_f32 v[160:161], v[132:133], s[36:37] op_sel_hi:[1,0]
	v_fma_f32 v129, -v162, v162, v163
	v_fma_f32 v130, -v160, v160, v161
	v_max_f32_e32 v129, 0, v129
	v_mul_f32_e32 v131, 0x4f800000, v128
	v_max_f32_e32 v130, 0, v130
	v_add_f32_e32 v129, 0x3727c5ac, v129
	v_cndmask_b32_e32 v128, v128, v131, vcc
	v_add_f32_e32 v130, 0x3727c5ac, v130
	v_mul_f32_e32 v131, 0x4f800000, v129
	v_sqrt_f32_e32 v133, v128
	v_cmp_gt_f32_e64 s[0:1], s63, v129
	v_mul_f32_e32 v132, 0x4f800000, v130
	v_cmp_gt_f32_e64 s[8:9], s63, v130
	v_cndmask_b32_e64 v129, v129, v131, s[0:1]
	v_sqrt_f32_e32 v131, v129
	v_cndmask_b32_e64 v130, v130, v132, s[8:9]
	v_sqrt_f32_e32 v132, v130
	v_add_u32_e32 v138, -1, v133
	v_add_u32_e32 v139, 1, v133
	v_fma_f32 v140, -v138, v133, v128
	v_fma_f32 v141, -v139, v133, v128
	v_add_u32_e32 v142, -1, v131
	v_cmp_ge_f32_e64 s[10:11], 0, v140
	v_add_u32_e32 v164, -1, v132
	v_add_u32_e32 v143, 1, v131
	v_cndmask_b32_e64 v133, v133, v138, s[10:11]
	v_fma_f32 v138, -v142, v131, v129
	v_cmp_lt_f32_e64 s[10:11], 0, v141
	v_fma_f32 v168, -v164, v132, v130
	v_add_u32_e32 v165, 1, v132
	v_cndmask_b32_e64 v133, v133, v139, s[10:11]
	v_cmp_ge_f32_e64 s[10:11], 0, v138
	v_fma_f32 v140, -v143, v131, v129
	v_fma_f32 v169, -v165, v132, v130
	v_cndmask_b32_e64 v131, v131, v142, s[10:11]
	v_cmp_ge_f32_e64 s[10:11], 0, v168
	v_mul_f32_e32 v138, 0x37800000, v133
	v_cndmask_b32_e32 v133, v133, v138, vcc
	v_cndmask_b32_e64 v132, v132, v164, s[10:11]
	v_cmp_lt_f32_e64 s[10:11], 0, v140
	v_cmp_class_f32_e32 vcc, v128, v189
	v_pk_mul_f32 v[170:171], v[136:137], s[36:37] op_sel_hi:[1,0]
	v_cndmask_b32_e64 v131, v131, v143, s[10:11]
	v_cmp_lt_f32_e64 s[10:11], 0, v169
	v_mul_f32_e32 v138, 0x37800000, v131
	v_cndmask_b32_e32 v128, v133, v128, vcc
	v_cndmask_b32_e64 v132, v132, v165, s[10:11]
	v_cndmask_b32_e64 v131, v131, v138, s[0:1]
	v_div_scale_f32 v133, s[0:1], v128, v128, 1.0
	v_mul_f32_e32 v139, 0x37800000, v132
	v_cmp_class_f32_e64 s[0:1], v129, v189
	v_cndmask_b32_e64 v132, v132, v139, s[8:9]
	v_div_scale_f32 v138, vcc, 1.0, v128, 1.0
	v_cndmask_b32_e64 v129, v131, v129, s[0:1]
	v_cmp_class_f32_e64 s[0:1], v130, v189
	v_rcp_f32_e32 v131, v133
	s_nop 0
	v_cndmask_b32_e64 v130, v132, v130, s[0:1]
	v_div_scale_f32 v132, s[0:1], v129, v129, 1.0
	v_div_scale_f32 v140, s[8:9], v130, v130, 1.0
	v_rcp_f32_e32 v141, v132
	v_rcp_f32_e32 v142, v140
	v_fma_f32 v143, -v133, v131, 1.0
	v_fmac_f32_e32 v131, v143, v131
	v_fma_f32 v143, -v132, v141, 1.0
	v_div_scale_f32 v139, s[0:1], 1.0, v129, 1.0
	v_fma_f32 v164, -v140, v142, 1.0
	v_mul_f32_e32 v165, v138, v131
	v_fmac_f32_e32 v141, v143, v141
	v_fmac_f32_e32 v142, v164, v142
	v_fma_f32 v143, -v133, v165, v138
	v_mul_f32_e32 v164, v139, v141
	v_fmac_f32_e32 v165, v143, v131
	v_fma_f32 v143, -v132, v164, v139
	v_fma_f32 v133, -v133, v165, v138
	v_fmac_f32_e32 v164, v143, v141
	v_div_fmas_f32 v131, v133, v131, v165
	v_fma_f32 v132, -v132, v164, v139
	s_mov_b64 vcc, s[0:1]
	v_div_fixup_f32 v184, v131, v128, 1.0
	v_div_fmas_f32 v128, v132, v141, v164
	v_div_fixup_f32 v176, v128, v129, 1.0
	v_lshl_add_u64 v[128:129], v[192:193], 3, s[20:21]
	s_nop 0
	v_pk_mul_f32 v[164:165], v[134:135], s[36:37] op_sel_hi:[1,0]
	v_div_scale_f32 v131, vcc, 1.0, v130, 1.0
	v_fma_f32 v133, -v164, v164, v165
	v_max_f32_e32 v133, 0, v133
	v_add_f32_e32 v133, 0x3727c5ac, v133
	v_mul_f32_e32 v134, 0x4f800000, v133
	v_cmp_gt_f32_e64 s[0:1], s63, v133
	v_mul_f32_e32 v132, v131, v142
	v_fma_f32 v135, -v140, v132, v131
	v_cndmask_b32_e64 v133, v133, v134, s[0:1]
	v_sqrt_f32_e32 v134, v133
	v_fmac_f32_e32 v132, v135, v142
	v_fma_f32 v131, -v140, v132, v131
	v_div_fmas_f32 v131, v131, v142, v132
	v_add_u32_e32 v135, -1, v134
	v_fma_f32 v138, -v135, v134, v133
	v_cmp_ge_f32_e64 s[8:9], 0, v138
	v_add_u32_e32 v138, 1, v134
	v_div_fixup_f32 v174, v131, v130, 1.0
	v_cndmask_b32_e64 v135, v134, v135, s[8:9]
	v_fma_f32 v134, -v138, v134, v133
	v_cmp_lt_f32_e64 s[8:9], 0, v134
	s_nop 1
	v_cndmask_b32_e64 v134, v135, v138, s[8:9]
	v_mul_f32_e32 v135, 0x37800000, v134
	v_cndmask_b32_e64 v134, v134, v135, s[0:1]
	v_cmp_class_f32_e64 s[0:1], v133, v189
	s_nop 1
	v_cndmask_b32_e64 v133, v134, v133, s[0:1]
	v_div_scale_f32 v134, s[0:1], v133, v133, 1.0
	v_rcp_f32_e32 v135, v134
	v_div_scale_f32 v132, vcc, 1.0, v133, 1.0
	v_fma_f32 v130, -v134, v135, 1.0
	v_fmac_f32_e32 v135, v130, v135
	v_lshl_add_u64 v[130:131], v[206:207], 3, s[20:21]
	s_nop 0
	v_lshl_add_u64 v[130:131], v[204:205], 3, s[20:21]
	s_nop 0
	v_fma_f32 v130, -v170, v170, v171
	v_max_f32_e32 v130, 0, v130
	v_add_f32_e32 v130, 0x3727c5ac, v130
	v_mul_f32_e32 v131, 0x4f800000, v130
	v_cmp_gt_f32_e64 s[0:1], s63, v130
	v_mul_f32_e32 v138, v132, v135
	v_fma_f32 v136, -v134, v138, v132
	v_cndmask_b32_e64 v130, v130, v131, s[0:1]
	v_sqrt_f32_e32 v131, v130
	v_fmac_f32_e32 v138, v136, v135
	v_fma_f32 v132, -v134, v138, v132
	v_div_fmas_f32 v132, v132, v135, v138
	v_add_u32_e32 v134, -1, v131
	v_fma_f32 v136, -v134, v131, v130
	v_cmp_ge_f32_e64 s[8:9], 0, v136
	v_add_u32_e32 v136, 1, v131
	v_div_fixup_f32 v186, v132, v133, 1.0
	v_cndmask_b32_e64 v134, v131, v134, s[8:9]
	v_fma_f32 v131, -v136, v131, v130
	v_cmp_lt_f32_e64 s[8:9], 0, v131
	s_nop 0
	v_pk_mul_f32 v[168:169], v[248:249], s[36:37] op_sel_hi:[1,0]
	v_cndmask_b32_e64 v131, v134, v136, s[8:9]
	v_mul_f32_e32 v134, 0x37800000, v131
	v_cndmask_b32_e64 v131, v131, v134, s[0:1]
	v_cmp_class_f32_e64 s[0:1], v130, v189
	v_fma_f32 v128, -v168, v168, v169
	v_max_f32_e32 v128, 0, v128
	v_cndmask_b32_e64 v130, v131, v130, s[0:1]
	v_div_scale_f32 v131, s[0:1], v130, v130, 1.0
	v_rcp_f32_e32 v134, v131
	v_add_f32_e32 v128, 0x3727c5ac, v128
	v_mul_f32_e32 v129, 0x4f800000, v128
	v_cmp_gt_f32_e64 s[0:1], s63, v128
	v_fma_f32 v132, -v131, v134, 1.0
	v_fmac_f32_e32 v134, v132, v134
	v_cndmask_b32_e64 v128, v128, v129, s[0:1]
	v_div_scale_f32 v132, vcc, 1.0, v130, 1.0
	v_sqrt_f32_e32 v129, v128
	v_mul_f32_e32 v133, v132, v134
	v_fma_f32 v135, -v131, v133, v132
	v_fmac_f32_e32 v133, v135, v134
	v_fma_f32 v131, -v131, v133, v132
	v_add_u32_e32 v132, -1, v129
	v_fma_f32 v135, -v132, v129, v128
	v_cmp_ge_f32_e64 s[8:9], 0, v135
	v_add_u32_e32 v135, 1, v129
	v_pk_mul_f32 v[178:179], v[246:247], s[36:37] op_sel_hi:[1,0]
	v_cndmask_b32_e64 v132, v129, v132, s[8:9]
	v_fma_f32 v129, -v135, v129, v128
	v_cmp_lt_f32_e64 s[8:9], 0, v129
	v_fma_f32 v172, -v178, v178, v179
	v_max_f32_e32 v172, 0, v172
	v_cndmask_b32_e64 v129, v132, v135, s[8:9]
	v_mul_f32_e32 v132, 0x37800000, v129
	v_cndmask_b32_e64 v129, v129, v132, s[0:1]
	v_cmp_class_f32_e64 s[0:1], v128, v189
	v_add_f32_e32 v172, 0x3727c5ac, v172
	v_mul_f32_e32 v173, 0x4f800000, v172
	v_cndmask_b32_e64 v180, v129, v128, s[0:1]
	v_div_scale_f32 v188, s[0:1], v180, v180, 1.0
	v_rcp_f32_e32 v190, v188
	v_div_fmas_f32 v128, v131, v134, v133
	v_lshlrev_b64 v[132:133], 2, v[208:209]
	v_div_fixup_f32 v182, v128, v130, 1.0
	v_fma_f32 v128, -v188, v190, 1.0
	v_lshl_add_u64 v[134:135], s[82:83], 0, v[132:133]
	v_fmac_f32_e32 v190, v128, v190
	global_load_dwordx4 v[128:131], v[134:135], off offset:16
	global_load_dwordx4 v[140:143], v[134:135], off
	v_lshl_add_u64 v[136:137], s[26:27], 0, v[132:133]
	global_load_dwordx4 v[132:135], v[136:137], off offset:16
	s_nop 0
	global_load_dwordx4 v[136:139], v[136:137], off
	v_cmp_gt_f32_e64 s[0:1], s63, v172
	v_div_scale_f32 v191, vcc, 1.0, v180, 1.0
	s_nop 0
	v_cndmask_b32_e64 v172, v172, v173, s[0:1]
	v_sqrt_f32_e32 v173, v172
	v_mul_f32_e32 v212, v191, v190
	v_fma_f32 v213, -v188, v212, v191
	v_fmac_f32_e32 v212, v213, v190
	v_fma_f32 v188, -v188, v212, v191
	v_add_u32_e32 v191, -1, v173
	v_fma_f32 v213, -v191, v173, v172
	v_cmp_ge_f32_e64 s[8:9], 0, v213
	v_add_u32_e32 v213, 1, v173
	s_waitcnt vmcnt(0)
	v_pk_fma_f32 v[120:121], v[166:167], v[128:129], v[120:121] op_sel_hi:[0,1,1] neg_lo:[1,0,0] neg_hi:[1,0,0]
	v_cndmask_b32_e64 v191, v173, v191, s[8:9]
	v_fma_f32 v173, -v213, v173, v172
	v_cmp_lt_f32_e64 s[8:9], 0, v173
	v_pk_fma_f32 v[124:125], v[166:167], v[140:141], v[124:125] op_sel_hi:[0,1,1] neg_lo:[1,0,0] neg_hi:[1,0,0]
	v_pk_fma_f32 v[126:127], v[166:167], v[142:143], v[126:127] op_sel_hi:[0,1,1] neg_lo:[1,0,0] neg_hi:[1,0,0]
	v_cndmask_b32_e64 v173, v191, v213, s[8:9]
	v_mul_f32_e32 v191, 0x37800000, v173
	v_cndmask_b32_e64 v173, v173, v191, s[0:1]
	v_cmp_class_f32_e64 s[0:1], v172, v189
	v_pk_fma_f32 v[126:127], v[184:185], v[126:127], v[138:139] op_sel_hi:[0,1,1]
	v_pk_fma_f32 v[124:125], v[184:185], v[124:125], v[136:137] op_sel_hi:[0,1,1]
	v_cndmask_b32_e64 v191, v173, v172, s[0:1]
	v_div_scale_f32 v213, s[0:1], v191, v191, 1.0
	v_rcp_f32_e32 v214, v213
	v_div_fmas_f32 v172, v188, v190, v212
	v_div_fixup_f32 v190, v172, v180, 1.0
	v_div_scale_f32 v180, vcc, 1.0, v191, 1.0
	v_fma_f32 v172, -v213, v214, 1.0
	v_fmac_f32_e32 v214, v172, v214
	v_pk_mul_f32 v[172:173], v[244:245], s[36:37] op_sel_hi:[1,0]
	v_mul_f32_e32 v188, v180, v214
	v_fma_f32 v210, -v172, v172, v173
	v_max_f32_e32 v210, 0, v210
	v_add_f32_e32 v210, 0x3727c5ac, v210
	v_mul_f32_e32 v211, 0x4f800000, v210
	v_cmp_gt_f32_e64 s[0:1], s63, v210
	v_fma_f32 v212, -v213, v188, v180
	v_fmac_f32_e32 v188, v212, v214
	v_cndmask_b32_e64 v210, v210, v211, s[0:1]
	v_sqrt_f32_e32 v211, v210
	v_fma_f32 v180, -v213, v188, v180
	v_pk_fma_f32 v[122:123], v[166:167], v[130:131], v[122:123] op_sel_hi:[0,1,1] neg_lo:[1,0,0] neg_hi:[1,0,0]
	v_pk_fma_f32 v[120:121], v[184:185], v[120:121], v[132:133] op_sel_hi:[0,1,1]
	v_add_u32_e32 v212, -1, v211
	v_fma_f32 v213, -v212, v211, v210
	v_cmp_ge_f32_e64 s[8:9], 0, v213
	v_add_u32_e32 v213, 1, v211
	v_pk_fma_f32 v[122:123], v[184:185], v[122:123], v[134:135] op_sel_hi:[0,1,1]
	v_cndmask_b32_e64 v212, v211, v212, s[8:9]
	v_fma_f32 v211, -v213, v211, v210
	v_cmp_lt_f32_e64 s[8:9], 0, v211
	v_max_f32_e32 v124, 0, v124
	v_max_f32_e32 v120, 0, v120
	v_cndmask_b32_e64 v211, v212, v213, s[8:9]
	v_max_f32_e32 v125, 0, v125
	v_max_f32_e32 v121, 0, v121
	v_max_f32_e32 v126, 0, v126
	v_max_f32_e32 v127, 0, v127
	v_mul_f32_e32 v212, 0x37800000, v211
	v_pk_mul_f32 v[124:125], v[124:125], v[124:125]
	v_pk_mul_f32 v[120:121], v[120:121], v[120:121]
	v_max_f32_e32 v122, 0, v122
	v_max_f32_e32 v123, 0, v123
	v_pk_mul_f32 v[126:127], v[126:127], v[126:127]
	v_pk_fma_f32 v[116:117], v[162:163], v[140:141], v[116:117] op_sel_hi:[0,1,1] neg_lo:[1,0,0] neg_hi:[1,0,0]
	v_pk_fma_f32 v[112:113], v[162:163], v[128:129], v[112:113] op_sel_hi:[0,1,1] neg_lo:[1,0,0] neg_hi:[1,0,0]
	v_cndmask_b32_e64 v211, v211, v212, s[0:1]
	v_cmp_class_f32_e64 s[0:1], v210, v189
	v_pk_mul_f32 v[122:123], v[122:123], v[122:123]
	v_cvt_pk_bf16_f32 v124, v124, v125
	v_cvt_pk_bf16_f32 v125, v126, v127
	v_cvt_pk_bf16_f32 v126, v120, v121
	v_lshlrev_b64 v[120:121], 14, v[202:203]
	v_pk_fma_f32 v[116:117], v[176:177], v[116:117], v[136:137] op_sel_hi:[0,1,1]
	v_pk_fma_f32 v[114:115], v[162:163], v[130:131], v[114:115] op_sel_hi:[0,1,1] neg_lo:[1,0,0] neg_hi:[1,0,0]
	v_pk_fma_f32 v[112:113], v[176:177], v[112:113], v[132:133] op_sel_hi:[0,1,1]
	v_cndmask_b32_e64 v210, v211, v210, s[0:1]
	v_cvt_pk_bf16_f32 v127, v122, v123
	v_lshl_add_u64 v[120:121], s[50:51], 0, v[120:121]
	v_lshlrev_b64 v[122:123], 1, v[208:209]
	v_pk_fma_f32 v[118:119], v[162:163], v[142:143], v[118:119] op_sel_hi:[0,1,1] neg_lo:[1,0,0] neg_hi:[1,0,0]
	v_pk_fma_f32 v[114:115], v[176:177], v[114:115], v[134:135] op_sel_hi:[0,1,1]
	v_max_f32_e32 v116, 0, v116
	v_max_f32_e32 v112, 0, v112
	v_max_f32_e32 v117, 0, v117
	v_max_f32_e32 v113, 0, v113
	v_div_scale_f32 v211, s[0:1], v210, v210, 1.0
	v_lshl_add_u64 v[120:121], v[120:121], 0, v[122:123]
	v_pk_fma_f32 v[118:119], v[176:177], v[118:119], v[138:139] op_sel_hi:[0,1,1]
	v_pk_mul_f32 v[116:117], v[116:117], v[116:117]
	v_pk_mul_f32 v[112:113], v[112:113], v[112:113]
	v_max_f32_e32 v114, 0, v114
	v_max_f32_e32 v115, 0, v115
	v_pk_fma_f32 v[108:109], v[160:161], v[140:141], v[108:109] op_sel_hi:[0,1,1] neg_lo:[1,0,0] neg_hi:[1,0,0]
	v_pk_fma_f32 v[104:105], v[160:161], v[128:129], v[104:105] op_sel_hi:[0,1,1] neg_lo:[1,0,0] neg_hi:[1,0,0]
	v_rcp_f32_e32 v212, v211
	global_store_dwordx4 v[120:121], v[124:127], off
	v_max_f32_e32 v118, 0, v118
	v_max_f32_e32 v119, 0, v119
	v_pk_mul_f32 v[124:125], v[114:115], v[114:115]
	v_cvt_pk_bf16_f32 v114, v116, v117
	v_cvt_pk_bf16_f32 v116, v112, v113
	v_lshlrev_b64 v[112:113], 14, v[200:201]
	v_pk_fma_f32 v[108:109], v[174:175], v[108:109], v[136:137] op_sel_hi:[0,1,1]
	v_pk_fma_f32 v[106:107], v[160:161], v[130:131], v[106:107] op_sel_hi:[0,1,1] neg_lo:[1,0,0] neg_hi:[1,0,0]
	v_pk_fma_f32 v[104:105], v[174:175], v[104:105], v[132:133] op_sel_hi:[0,1,1]
	v_pk_mul_f32 v[118:119], v[118:119], v[118:119]
	v_lshl_add_u64 v[112:113], s[50:51], 0, v[112:113]
	v_pk_fma_f32 v[110:111], v[160:161], v[142:143], v[110:111] op_sel_hi:[0,1,1] neg_lo:[1,0,0] neg_hi:[1,0,0]
	v_pk_fma_f32 v[106:107], v[174:175], v[106:107], v[134:135] op_sel_hi:[0,1,1]
	v_max_f32_e32 v108, 0, v108
	v_max_f32_e32 v104, 0, v104
	v_max_f32_e32 v109, 0, v109
	v_max_f32_e32 v105, 0, v105
	v_cvt_pk_bf16_f32 v115, v118, v119
	v_cvt_pk_bf16_f32 v117, v124, v125
	v_lshl_add_u64 v[112:113], v[112:113], 0, v[122:123]
	v_pk_fma_f32 v[110:111], v[174:175], v[110:111], v[138:139] op_sel_hi:[0,1,1]
	v_pk_mul_f32 v[108:109], v[108:109], v[108:109]
	v_pk_mul_f32 v[104:105], v[104:105], v[104:105]
	v_max_f32_e32 v106, 0, v106
	v_max_f32_e32 v107, 0, v107
	v_pk_fma_f32 v[100:101], v[164:165], v[140:141], v[100:101] op_sel_hi:[0,1,1] neg_lo:[1,0,0] neg_hi:[1,0,0]
	v_pk_fma_f32 v[96:97], v[164:165], v[128:129], v[96:97] op_sel_hi:[0,1,1] neg_lo:[1,0,0] neg_hi:[1,0,0]
	v_div_fmas_f32 v180, v180, v214, v188
	global_store_dwordx4 v[112:113], v[114:117], off
	v_max_f32_e32 v110, 0, v110
	v_max_f32_e32 v111, 0, v111
	v_pk_mul_f32 v[114:115], v[106:107], v[106:107]
	v_cvt_pk_bf16_f32 v106, v108, v109
	v_cvt_pk_bf16_f32 v108, v104, v105
	v_lshlrev_b64 v[104:105], 14, v[198:199]
	v_pk_fma_f32 v[100:101], v[186:187], v[100:101], v[136:137] op_sel_hi:[0,1,1]
	v_pk_fma_f32 v[98:99], v[164:165], v[130:131], v[98:99] op_sel_hi:[0,1,1] neg_lo:[1,0,0] neg_hi:[1,0,0]
	v_pk_fma_f32 v[96:97], v[186:187], v[96:97], v[132:133] op_sel_hi:[0,1,1]
	v_div_fixup_f32 v188, v180, v191, 1.0
	v_fma_f32 v180, -v211, v212, 1.0
	v_pk_mul_f32 v[110:111], v[110:111], v[110:111]
	v_lshl_add_u64 v[104:105], s[50:51], 0, v[104:105]
	v_pk_fma_f32 v[102:103], v[164:165], v[142:143], v[102:103] op_sel_hi:[0,1,1] neg_lo:[1,0,0] neg_hi:[1,0,0]
	v_pk_fma_f32 v[98:99], v[186:187], v[98:99], v[134:135] op_sel_hi:[0,1,1]
	v_max_f32_e32 v100, 0, v100
	v_max_f32_e32 v96, 0, v96
	v_max_f32_e32 v101, 0, v101
	v_max_f32_e32 v97, 0, v97
	v_fmac_f32_e32 v212, v180, v212
	v_div_scale_f32 v180, vcc, 1.0, v210, 1.0
	v_cvt_pk_bf16_f32 v107, v110, v111
	v_cvt_pk_bf16_f32 v109, v114, v115
	v_lshl_add_u64 v[104:105], v[104:105], 0, v[122:123]
	v_pk_fma_f32 v[102:103], v[186:187], v[102:103], v[138:139] op_sel_hi:[0,1,1]
	v_pk_mul_f32 v[100:101], v[100:101], v[100:101]
	v_pk_mul_f32 v[96:97], v[96:97], v[96:97]
	v_max_f32_e32 v98, 0, v98
	v_max_f32_e32 v99, 0, v99
	v_pk_fma_f32 v[92:93], v[170:171], v[140:141], v[92:93] op_sel_hi:[0,1,1] neg_lo:[1,0,0] neg_hi:[1,0,0]
	v_pk_fma_f32 v[88:89], v[170:171], v[128:129], v[88:89] op_sel_hi:[0,1,1] neg_lo:[1,0,0] neg_hi:[1,0,0]
	v_mul_f32_e32 v191, v180, v212
	global_store_dwordx4 v[104:105], v[106:109], off
	v_max_f32_e32 v102, 0, v102
	v_max_f32_e32 v103, 0, v103
	v_pk_mul_f32 v[106:107], v[98:99], v[98:99]
	v_cvt_pk_bf16_f32 v98, v100, v101
	v_cvt_pk_bf16_f32 v100, v96, v97
	v_lshlrev_b64 v[96:97], 14, v[196:197]
	v_pk_fma_f32 v[92:93], v[182:183], v[92:93], v[136:137] op_sel_hi:[0,1,1]
	v_pk_fma_f32 v[90:91], v[170:171], v[130:131], v[90:91] op_sel_hi:[0,1,1] neg_lo:[1,0,0] neg_hi:[1,0,0]
	v_pk_fma_f32 v[88:89], v[182:183], v[88:89], v[132:133] op_sel_hi:[0,1,1]
	v_fma_f32 v213, -v211, v191, v180
	v_pk_mul_f32 v[102:103], v[102:103], v[102:103]
	v_lshl_add_u64 v[96:97], s[50:51], 0, v[96:97]
	v_pk_fma_f32 v[94:95], v[170:171], v[142:143], v[94:95] op_sel_hi:[0,1,1] neg_lo:[1,0,0] neg_hi:[1,0,0]
	v_pk_fma_f32 v[90:91], v[182:183], v[90:91], v[134:135] op_sel_hi:[0,1,1]
	v_max_f32_e32 v92, 0, v92
	v_max_f32_e32 v88, 0, v88
	v_max_f32_e32 v93, 0, v93
	v_max_f32_e32 v89, 0, v89
	v_fmac_f32_e32 v191, v213, v212
	v_cvt_pk_bf16_f32 v99, v102, v103
	v_cvt_pk_bf16_f32 v101, v106, v107
	v_lshl_add_u64 v[96:97], v[96:97], 0, v[122:123]
	v_pk_fma_f32 v[94:95], v[182:183], v[94:95], v[138:139] op_sel_hi:[0,1,1]
	v_pk_mul_f32 v[92:93], v[92:93], v[92:93]
	v_pk_mul_f32 v[88:89], v[88:89], v[88:89]
	v_max_f32_e32 v90, 0, v90
	v_max_f32_e32 v91, 0, v91
	v_pk_fma_f32 v[84:85], v[168:169], v[140:141], v[84:85] op_sel_hi:[0,1,1] neg_lo:[1,0,0] neg_hi:[1,0,0]
	v_pk_fma_f32 v[80:81], v[168:169], v[128:129], v[80:81] op_sel_hi:[0,1,1] neg_lo:[1,0,0] neg_hi:[1,0,0]
	global_store_dwordx4 v[96:97], v[98:101], off
	v_max_f32_e32 v94, 0, v94
	v_max_f32_e32 v95, 0, v95
	v_pk_mul_f32 v[98:99], v[90:91], v[90:91]
	v_cvt_pk_bf16_f32 v90, v92, v93
	v_cvt_pk_bf16_f32 v92, v88, v89
	v_lshlrev_b64 v[88:89], 14, v[194:195]
	v_pk_fma_f32 v[84:85], v[84:85], v[190:191], v[136:137] op_sel_hi:[1,0,1]
	v_pk_fma_f32 v[82:83], v[168:169], v[130:131], v[82:83] op_sel_hi:[0,1,1] neg_lo:[1,0,0] neg_hi:[1,0,0]
	v_pk_fma_f32 v[80:81], v[190:191], v[80:81], v[132:133] op_sel_hi:[0,1,1]
	v_pk_mul_f32 v[94:95], v[94:95], v[94:95]
	v_lshl_add_u64 v[88:89], s[50:51], 0, v[88:89]
	v_pk_fma_f32 v[86:87], v[168:169], v[142:143], v[86:87] op_sel_hi:[0,1,1] neg_lo:[1,0,0] neg_hi:[1,0,0]
	v_pk_fma_f32 v[82:83], v[190:191], v[82:83], v[134:135] op_sel_hi:[0,1,1]
	v_max_f32_e32 v84, 0, v84
	v_max_f32_e32 v80, 0, v80
	v_max_f32_e32 v85, 0, v85
	v_max_f32_e32 v81, 0, v81
	v_cvt_pk_bf16_f32 v91, v94, v95
	v_cvt_pk_bf16_f32 v93, v98, v99
	v_lshl_add_u64 v[88:89], v[88:89], 0, v[122:123]
	v_pk_fma_f32 v[86:87], v[86:87], v[190:191], v[138:139] op_sel_hi:[1,0,1]
	v_pk_mul_f32 v[84:85], v[84:85], v[84:85]
	v_pk_mul_f32 v[80:81], v[80:81], v[80:81]
	v_max_f32_e32 v82, 0, v82
	v_max_f32_e32 v83, 0, v83
	global_store_dwordx4 v[88:89], v[90:93], off
	v_max_f32_e32 v86, 0, v86
	v_max_f32_e32 v87, 0, v87
	v_pk_mul_f32 v[90:91], v[82:83], v[82:83]
	v_cvt_pk_bf16_f32 v82, v84, v85
	v_cvt_pk_bf16_f32 v84, v80, v81
	v_lshlrev_b64 v[80:81], 14, v[192:193]
	v_pk_fma_f32 v[76:77], v[178:179], v[140:141], v[76:77] op_sel_hi:[0,1,1] neg_lo:[1,0,0] neg_hi:[1,0,0]
	v_pk_fma_f32 v[72:73], v[178:179], v[128:129], v[72:73] op_sel_hi:[0,1,1] neg_lo:[1,0,0] neg_hi:[1,0,0]
	v_pk_mul_f32 v[86:87], v[86:87], v[86:87]
	v_lshl_add_u64 v[80:81], s[50:51], 0, v[80:81]
	v_pk_fma_f32 v[78:79], v[178:179], v[142:143], v[78:79] op_sel_hi:[0,1,1] neg_lo:[1,0,0] neg_hi:[1,0,0]
	v_pk_fma_f32 v[76:77], v[76:77], v[188:189], v[136:137] op_sel_hi:[1,0,1]
	v_pk_fma_f32 v[72:73], v[72:73], v[188:189], v[132:133] op_sel_hi:[1,0,1]
	v_cvt_pk_bf16_f32 v83, v86, v87
	v_cvt_pk_bf16_f32 v85, v90, v91
	v_lshl_add_u64 v[80:81], v[80:81], 0, v[122:123]
	v_pk_fma_f32 v[78:79], v[78:79], v[188:189], v[138:139] op_sel_hi:[1,0,1]
	v_pk_fma_f32 v[74:75], v[178:179], v[130:131], v[74:75] op_sel_hi:[0,1,1] neg_lo:[1,0,0] neg_hi:[1,0,0]
	v_max_f32_e32 v76, 0, v76
	v_max_f32_e32 v72, 0, v72
	v_max_f32_e32 v77, 0, v77
	v_max_f32_e32 v73, 0, v73
	global_store_dwordx4 v[80:81], v[82:85], off
	v_pk_fma_f32 v[74:75], v[74:75], v[188:189], v[134:135] op_sel_hi:[1,0,1]
	v_pk_mul_f32 v[76:77], v[76:77], v[76:77]
	v_pk_mul_f32 v[82:83], v[72:73], v[72:73]
	v_max_f32_e32 v72, 0, v78
	v_max_f32_e32 v73, 0, v79
	v_max_f32_e32 v74, 0, v74
	v_max_f32_e32 v75, 0, v75
	v_pk_mul_f32 v[78:79], v[72:73], v[72:73]
	v_cvt_pk_bf16_f32 v72, v76, v77
	v_lshlrev_b64 v[76:77], 14, v[206:207]
	v_fma_f32 v180, -v211, v191, v180
	v_pk_mul_f32 v[84:85], v[74:75], v[74:75]
	v_lshl_add_u64 v[76:77], s[50:51], 0, v[76:77]
	v_div_fmas_f32 v180, v180, v212, v191
	v_cvt_pk_bf16_f32 v73, v78, v79
	v_cvt_pk_bf16_f32 v74, v82, v83
	v_cvt_pk_bf16_f32 v75, v84, v85
	v_lshl_add_u64 v[82:83], v[76:77], 0, v[122:123]
	v_div_fixup_f32 v180, v180, v210, 1.0
	global_store_dwordx4 v[82:83], v[72:75], off
	v_pk_fma_f32 v[68:69], v[140:141], v[172:173], v[68:69] op_sel_hi:[1,0,1] neg_lo:[1,0,0] neg_hi:[1,0,0]
	v_pk_fma_f32 v[64:65], v[172:173], v[128:129], v[64:65] op_sel_hi:[0,1,1] neg_lo:[1,0,0] neg_hi:[1,0,0]
	v_xor_b32_e32 v73, 0x80000000, v143
	v_xor_b32_e32 v72, 0x80000000, v142
	v_pk_fma_f32 v[70:71], v[72:73], v[172:173], v[70:71] op_sel_hi:[1,0,1]
	v_pk_fma_f32 v[68:69], v[68:69], v[180:181], v[136:137] op_sel_hi:[1,0,1]
	v_pk_fma_f32 v[64:65], v[64:65], v[180:181], v[132:133] op_sel_hi:[1,0,1]
	v_pk_fma_f32 v[70:71], v[70:71], v[180:181], v[138:139] op_sel_hi:[1,0,1]
	v_pk_fma_f32 v[66:67], v[172:173], v[130:131], v[66:67] op_sel_hi:[0,1,1] neg_lo:[1,0,0] neg_hi:[1,0,0]
	v_max_f32_e32 v68, 0, v68
	v_max_f32_e32 v64, 0, v64
	v_max_f32_e32 v69, 0, v69
	v_max_f32_e32 v65, 0, v65
	v_pk_fma_f32 v[66:67], v[66:67], v[180:181], v[134:135] op_sel_hi:[1,0,1]
	v_pk_mul_f32 v[68:69], v[68:69], v[68:69]
	v_pk_mul_f32 v[72:73], v[64:65], v[64:65]
	v_max_f32_e32 v64, 0, v70
	v_max_f32_e32 v65, 0, v71
	v_max_f32_e32 v66, 0, v66
	v_max_f32_e32 v67, 0, v67
	v_pk_mul_f32 v[70:71], v[64:65], v[64:65]
	v_cvt_pk_bf16_f32 v64, v68, v69
	v_lshlrev_b64 v[68:69], 14, v[204:205]
	v_pk_mul_f32 v[74:75], v[66:67], v[66:67]
	v_lshl_add_u64 v[68:69], s[50:51], 0, v[68:69]
	v_cvt_pk_bf16_f32 v65, v70, v71
	v_cvt_pk_bf16_f32 v66, v72, v73
	v_cvt_pk_bf16_f32 v67, v74, v75
	v_lshl_add_u64 v[84:85], v[68:69], 0, v[122:123]
	global_store_dwordx4 v[84:85], v[64:67], off
	s_and_b64 vcc, exec, s[6:7]
	s_mov_b64 s[0:1], -1
	v_or_b32_e32 v64, 0x80, v208
	v_ashrrev_i32_e32 v65, 31, v64
	v_lshlrev_b64 v[64:65], 2, v[64:65]
	v_lshl_add_u64 v[66:67], s[82:83], 0, v[64:65]
	v_lshl_add_u64 v[64:65], s[26:27], 0, v[64:65]
	global_load_dwordx4 v[72:75], v[66:67], off
	global_load_dwordx4 v[76:79], v[64:65], off
	global_load_dwordx4 v[68:71], v[66:67], off offset:16
	s_nop 0
	global_load_dwordx4 v[64:67], v[64:65], off offset:16
	s_waitcnt vmcnt(0)
	v_pk_fma_f32 v[56:57], v[166:167], v[68:69], v[56:57] op_sel_hi:[0,1,1] neg_lo:[1,0,0] neg_hi:[1,0,0]
	v_pk_fma_f32 v[60:61], v[166:167], v[72:73], v[60:61] op_sel_hi:[0,1,1] neg_lo:[1,0,0] neg_hi:[1,0,0]
	v_pk_fma_f32 v[62:63], v[166:167], v[74:75], v[62:63] op_sel_hi:[0,1,1] neg_lo:[1,0,0] neg_hi:[1,0,0]
	v_pk_fma_f32 v[58:59], v[166:167], v[70:71], v[58:59] op_sel_hi:[0,1,1] neg_lo:[1,0,0] neg_hi:[1,0,0]
	v_pk_fma_f32 v[56:57], v[184:185], v[56:57], v[64:65] op_sel_hi:[0,1,1]
	v_pk_fma_f32 v[62:63], v[184:185], v[62:63], v[78:79] op_sel_hi:[0,1,1]
	v_pk_fma_f32 v[60:61], v[184:185], v[60:61], v[76:77] op_sel_hi:[0,1,1]
	v_pk_fma_f32 v[58:59], v[184:185], v[58:59], v[66:67] op_sel_hi:[0,1,1]
	v_max_f32_e32 v56, 0, v56
	v_max_f32_e32 v57, 0, v57
	v_max_f32_e32 v60, 0, v60
	v_max_f32_e32 v61, 0, v61
	v_pk_mul_f32 v[86:87], v[56:57], v[56:57]
	v_max_f32_e32 v56, 0, v62
	v_max_f32_e32 v58, 0, v58
	v_max_f32_e32 v57, 0, v63
	v_max_f32_e32 v59, 0, v59
	v_pk_fma_f32 v[48:49], v[162:163], v[68:69], v[48:49] op_sel_hi:[0,1,1] neg_lo:[1,0,0] neg_hi:[1,0,0]
	v_pk_mul_f32 v[60:61], v[60:61], v[60:61]
	v_pk_mul_f32 v[62:63], v[56:57], v[56:57]
	v_pk_mul_f32 v[90:91], v[58:59], v[58:59]
	v_pk_fma_f32 v[52:53], v[162:163], v[72:73], v[52:53] op_sel_hi:[0,1,1] neg_lo:[1,0,0] neg_hi:[1,0,0]
	v_pk_fma_f32 v[54:55], v[162:163], v[74:75], v[54:55] op_sel_hi:[0,1,1] neg_lo:[1,0,0] neg_hi:[1,0,0]
	v_pk_fma_f32 v[50:51], v[162:163], v[70:71], v[50:51] op_sel_hi:[0,1,1] neg_lo:[1,0,0] neg_hi:[1,0,0]
	v_pk_fma_f32 v[48:49], v[176:177], v[48:49], v[64:65] op_sel_hi:[0,1,1]
	v_cvt_pk_bf16_f32 v56, v60, v61
	v_cvt_pk_bf16_f32 v57, v62, v63
	v_cvt_pk_bf16_f32 v58, v86, v87
	v_cvt_pk_bf16_f32 v59, v90, v91
	v_pk_fma_f32 v[54:55], v[176:177], v[54:55], v[78:79] op_sel_hi:[0,1,1]
	v_pk_fma_f32 v[52:53], v[176:177], v[52:53], v[76:77] op_sel_hi:[0,1,1]
	v_pk_fma_f32 v[50:51], v[176:177], v[50:51], v[66:67] op_sel_hi:[0,1,1]
	v_max_f32_e32 v48, 0, v48
	v_max_f32_e32 v49, 0, v49
	global_store_dwordx4 v[120:121], v[56:59], off offset:256
	v_max_f32_e32 v52, 0, v52
	v_max_f32_e32 v53, 0, v53
	v_pk_mul_f32 v[56:57], v[48:49], v[48:49]
	v_max_f32_e32 v48, 0, v54
	v_max_f32_e32 v50, 0, v50
	v_max_f32_e32 v49, 0, v55
	v_max_f32_e32 v51, 0, v51
	v_pk_fma_f32 v[40:41], v[160:161], v[68:69], v[40:41] op_sel_hi:[0,1,1] neg_lo:[1,0,0] neg_hi:[1,0,0]
	v_pk_mul_f32 v[52:53], v[52:53], v[52:53]
	v_pk_mul_f32 v[54:55], v[48:49], v[48:49]
	v_pk_mul_f32 v[58:59], v[50:51], v[50:51]
	v_pk_fma_f32 v[44:45], v[160:161], v[72:73], v[44:45] op_sel_hi:[0,1,1] neg_lo:[1,0,0] neg_hi:[1,0,0]
	v_pk_fma_f32 v[46:47], v[160:161], v[74:75], v[46:47] op_sel_hi:[0,1,1] neg_lo:[1,0,0] neg_hi:[1,0,0]
	v_pk_fma_f32 v[42:43], v[160:161], v[70:71], v[42:43] op_sel_hi:[0,1,1] neg_lo:[1,0,0] neg_hi:[1,0,0]
	v_pk_fma_f32 v[40:41], v[174:175], v[40:41], v[64:65] op_sel_hi:[0,1,1]
	v_cvt_pk_bf16_f32 v48, v52, v53
	v_cvt_pk_bf16_f32 v49, v54, v55
	v_cvt_pk_bf16_f32 v50, v56, v57
	v_cvt_pk_bf16_f32 v51, v58, v59
	v_pk_fma_f32 v[46:47], v[174:175], v[46:47], v[78:79] op_sel_hi:[0,1,1]
	v_pk_fma_f32 v[44:45], v[174:175], v[44:45], v[76:77] op_sel_hi:[0,1,1]
	v_pk_fma_f32 v[42:43], v[174:175], v[42:43], v[66:67] op_sel_hi:[0,1,1]
	v_max_f32_e32 v40, 0, v40
	v_max_f32_e32 v41, 0, v41
	global_store_dwordx4 v[112:113], v[48:51], off offset:256
	v_max_f32_e32 v44, 0, v44
	v_max_f32_e32 v45, 0, v45
	v_pk_mul_f32 v[48:49], v[40:41], v[40:41]
	v_max_f32_e32 v40, 0, v46
	v_max_f32_e32 v42, 0, v42
	v_max_f32_e32 v41, 0, v47
	v_max_f32_e32 v43, 0, v43
	v_pk_fma_f32 v[32:33], v[164:165], v[68:69], v[32:33] op_sel_hi:[0,1,1] neg_lo:[1,0,0] neg_hi:[1,0,0]
	v_pk_mul_f32 v[44:45], v[44:45], v[44:45]
	v_pk_mul_f32 v[46:47], v[40:41], v[40:41]
	v_pk_mul_f32 v[50:51], v[42:43], v[42:43]
	v_pk_fma_f32 v[36:37], v[164:165], v[72:73], v[36:37] op_sel_hi:[0,1,1] neg_lo:[1,0,0] neg_hi:[1,0,0]
	v_pk_fma_f32 v[38:39], v[164:165], v[74:75], v[38:39] op_sel_hi:[0,1,1] neg_lo:[1,0,0] neg_hi:[1,0,0]
	v_pk_fma_f32 v[34:35], v[164:165], v[70:71], v[34:35] op_sel_hi:[0,1,1] neg_lo:[1,0,0] neg_hi:[1,0,0]
	v_pk_fma_f32 v[32:33], v[186:187], v[32:33], v[64:65] op_sel_hi:[0,1,1]
	v_cvt_pk_bf16_f32 v40, v44, v45
	v_cvt_pk_bf16_f32 v41, v46, v47
	v_cvt_pk_bf16_f32 v42, v48, v49
	v_cvt_pk_bf16_f32 v43, v50, v51
	v_pk_fma_f32 v[38:39], v[186:187], v[38:39], v[78:79] op_sel_hi:[0,1,1]
	v_pk_fma_f32 v[36:37], v[186:187], v[36:37], v[76:77] op_sel_hi:[0,1,1]
	v_pk_fma_f32 v[34:35], v[186:187], v[34:35], v[66:67] op_sel_hi:[0,1,1]
	v_max_f32_e32 v32, 0, v32
	v_max_f32_e32 v33, 0, v33
	global_store_dwordx4 v[104:105], v[40:43], off offset:256
	v_max_f32_e32 v36, 0, v36
	v_max_f32_e32 v37, 0, v37
	v_pk_mul_f32 v[40:41], v[32:33], v[32:33]
	v_max_f32_e32 v32, 0, v38
	v_max_f32_e32 v34, 0, v34
	v_max_f32_e32 v33, 0, v39
	v_max_f32_e32 v35, 0, v35
	v_pk_fma_f32 v[24:25], v[170:171], v[68:69], v[24:25] op_sel_hi:[0,1,1] neg_lo:[1,0,0] neg_hi:[1,0,0]
	v_pk_mul_f32 v[36:37], v[36:37], v[36:37]
	v_pk_mul_f32 v[38:39], v[32:33], v[32:33]
	v_pk_mul_f32 v[42:43], v[34:35], v[34:35]
	v_pk_fma_f32 v[28:29], v[170:171], v[72:73], v[28:29] op_sel_hi:[0,1,1] neg_lo:[1,0,0] neg_hi:[1,0,0]
	v_pk_fma_f32 v[30:31], v[170:171], v[74:75], v[30:31] op_sel_hi:[0,1,1] neg_lo:[1,0,0] neg_hi:[1,0,0]
	v_pk_fma_f32 v[26:27], v[170:171], v[70:71], v[26:27] op_sel_hi:[0,1,1] neg_lo:[1,0,0] neg_hi:[1,0,0]
	v_pk_fma_f32 v[24:25], v[182:183], v[24:25], v[64:65] op_sel_hi:[0,1,1]
	v_cvt_pk_bf16_f32 v32, v36, v37
	v_cvt_pk_bf16_f32 v33, v38, v39
	v_cvt_pk_bf16_f32 v34, v40, v41
	v_cvt_pk_bf16_f32 v35, v42, v43
	v_pk_fma_f32 v[30:31], v[182:183], v[30:31], v[78:79] op_sel_hi:[0,1,1]
	v_pk_fma_f32 v[28:29], v[182:183], v[28:29], v[76:77] op_sel_hi:[0,1,1]
	v_pk_fma_f32 v[26:27], v[182:183], v[26:27], v[66:67] op_sel_hi:[0,1,1]
	v_max_f32_e32 v24, 0, v24
	v_max_f32_e32 v25, 0, v25
	global_store_dwordx4 v[96:97], v[32:35], off offset:256
	v_max_f32_e32 v28, 0, v28
	v_max_f32_e32 v29, 0, v29
	v_pk_mul_f32 v[32:33], v[24:25], v[24:25]
	v_max_f32_e32 v24, 0, v30
	v_max_f32_e32 v26, 0, v26
	v_max_f32_e32 v25, 0, v31
	v_max_f32_e32 v27, 0, v27
	v_pk_fma_f32 v[16:17], v[168:169], v[68:69], v[16:17] op_sel_hi:[0,1,1] neg_lo:[1,0,0] neg_hi:[1,0,0]
	v_pk_mul_f32 v[28:29], v[28:29], v[28:29]
	v_pk_mul_f32 v[30:31], v[24:25], v[24:25]
	v_pk_mul_f32 v[34:35], v[26:27], v[26:27]
	v_pk_fma_f32 v[20:21], v[168:169], v[72:73], v[20:21] op_sel_hi:[0,1,1] neg_lo:[1,0,0] neg_hi:[1,0,0]
	v_pk_fma_f32 v[22:23], v[168:169], v[74:75], v[22:23] op_sel_hi:[0,1,1] neg_lo:[1,0,0] neg_hi:[1,0,0]
	v_pk_fma_f32 v[18:19], v[168:169], v[70:71], v[18:19] op_sel_hi:[0,1,1] neg_lo:[1,0,0] neg_hi:[1,0,0]
	v_pk_fma_f32 v[16:17], v[190:191], v[16:17], v[64:65] op_sel_hi:[0,1,1]
	v_cvt_pk_bf16_f32 v24, v28, v29
	v_cvt_pk_bf16_f32 v25, v30, v31
	v_cvt_pk_bf16_f32 v26, v32, v33
	v_cvt_pk_bf16_f32 v27, v34, v35
	v_pk_fma_f32 v[22:23], v[190:191], v[22:23], v[78:79] op_sel_hi:[0,1,1]
	v_pk_fma_f32 v[20:21], v[190:191], v[20:21], v[76:77] op_sel_hi:[0,1,1]
	v_pk_fma_f32 v[18:19], v[190:191], v[18:19], v[66:67] op_sel_hi:[0,1,1]
	v_max_f32_e32 v16, 0, v16
	v_max_f32_e32 v17, 0, v17
	global_store_dwordx4 v[88:89], v[24:27], off offset:256
	v_max_f32_e32 v20, 0, v20
	v_max_f32_e32 v21, 0, v21
	v_pk_mul_f32 v[24:25], v[16:17], v[16:17]
	v_max_f32_e32 v16, 0, v22
	v_max_f32_e32 v18, 0, v18
	v_max_f32_e32 v17, 0, v23
	v_max_f32_e32 v19, 0, v19
	v_pk_fma_f32 v[8:9], v[178:179], v[68:69], v[8:9] op_sel_hi:[0,1,1] neg_lo:[1,0,0] neg_hi:[1,0,0]
	v_pk_mul_f32 v[20:21], v[20:21], v[20:21]
	v_pk_mul_f32 v[22:23], v[16:17], v[16:17]
	v_pk_mul_f32 v[26:27], v[18:19], v[18:19]
	v_pk_fma_f32 v[12:13], v[178:179], v[72:73], v[12:13] op_sel_hi:[0,1,1] neg_lo:[1,0,0] neg_hi:[1,0,0]
	v_pk_fma_f32 v[14:15], v[178:179], v[74:75], v[14:15] op_sel_hi:[0,1,1] neg_lo:[1,0,0] neg_hi:[1,0,0]
	v_pk_fma_f32 v[10:11], v[178:179], v[70:71], v[10:11] op_sel_hi:[0,1,1] neg_lo:[1,0,0] neg_hi:[1,0,0]
	v_pk_fma_f32 v[8:9], v[188:189], v[8:9], v[64:65] op_sel_hi:[0,1,1]
	v_cvt_pk_bf16_f32 v16, v20, v21
	v_cvt_pk_bf16_f32 v17, v22, v23
	v_cvt_pk_bf16_f32 v18, v24, v25
	v_cvt_pk_bf16_f32 v19, v26, v27
	v_pk_fma_f32 v[14:15], v[188:189], v[14:15], v[78:79] op_sel_hi:[0,1,1]
	v_pk_fma_f32 v[12:13], v[188:189], v[12:13], v[76:77] op_sel_hi:[0,1,1]
	v_pk_fma_f32 v[10:11], v[188:189], v[10:11], v[66:67] op_sel_hi:[0,1,1]
	v_max_f32_e32 v8, 0, v8
	v_max_f32_e32 v9, 0, v9
	global_store_dwordx4 v[80:81], v[16:19], off offset:256
	v_max_f32_e32 v12, 0, v12
	v_max_f32_e32 v13, 0, v13
	v_pk_mul_f32 v[16:17], v[8:9], v[8:9]
	v_max_f32_e32 v8, 0, v14
	v_max_f32_e32 v10, 0, v10
	v_max_f32_e32 v9, 0, v15
	v_max_f32_e32 v11, 0, v11
	v_pk_fma_f32 v[0:1], v[172:173], v[68:69], v[0:1] op_sel_hi:[0,1,1] neg_lo:[1,0,0] neg_hi:[1,0,0]
	v_pk_mul_f32 v[12:13], v[12:13], v[12:13]
	v_pk_mul_f32 v[14:15], v[8:9], v[8:9]
	v_pk_mul_f32 v[18:19], v[10:11], v[10:11]
	v_pk_fma_f32 v[4:5], v[172:173], v[72:73], v[4:5] op_sel_hi:[0,1,1] neg_lo:[1,0,0] neg_hi:[1,0,0]
	v_pk_fma_f32 v[6:7], v[172:173], v[74:75], v[6:7] op_sel_hi:[0,1,1] neg_lo:[1,0,0] neg_hi:[1,0,0]
	v_pk_fma_f32 v[2:3], v[172:173], v[70:71], v[2:3] op_sel_hi:[0,1,1] neg_lo:[1,0,0] neg_hi:[1,0,0]
	v_pk_fma_f32 v[0:1], v[180:181], v[0:1], v[64:65] op_sel_hi:[0,1,1]
	v_cvt_pk_bf16_f32 v8, v12, v13
	v_cvt_pk_bf16_f32 v9, v14, v15
	v_cvt_pk_bf16_f32 v10, v16, v17
	v_cvt_pk_bf16_f32 v11, v18, v19
	v_pk_fma_f32 v[6:7], v[180:181], v[6:7], v[78:79] op_sel_hi:[0,1,1]
	v_pk_fma_f32 v[4:5], v[180:181], v[4:5], v[76:77] op_sel_hi:[0,1,1]
	v_pk_fma_f32 v[2:3], v[180:181], v[2:3], v[66:67] op_sel_hi:[0,1,1]
	v_max_f32_e32 v0, 0, v0
	v_max_f32_e32 v1, 0, v1
	global_store_dwordx4 v[82:83], v[8:11], off offset:256
	v_max_f32_e32 v4, 0, v4
	v_max_f32_e32 v5, 0, v5
	v_pk_mul_f32 v[8:9], v[0:1], v[0:1]
	v_max_f32_e32 v0, 0, v6
	v_max_f32_e32 v2, 0, v2
	v_max_f32_e32 v1, 0, v7
	v_max_f32_e32 v3, 0, v3
	v_pk_mul_f32 v[4:5], v[4:5], v[4:5]
	v_pk_mul_f32 v[6:7], v[0:1], v[0:1]
	v_pk_mul_f32 v[10:11], v[2:3], v[2:3]
	v_cvt_pk_bf16_f32 v0, v4, v5
	v_cvt_pk_bf16_f32 v1, v6, v7
	v_cvt_pk_bf16_f32 v2, v8, v9
	v_cvt_pk_bf16_f32 v3, v10, v11
	global_store_dwordx4 v[84:85], v[0:3], off offset:256
	s_cbranch_vccnz .LBB0_759
	s_andn2_b64 vcc, exec, s[24:25]
	s_cbranch_vccnz .LBB0_758
	s_barrier
	s_branch .LBB0_758

.LBB0_1392:
	v_lshl_add_u32 v202, s62, 8, v175
	v_ashrrev_i32_e32 v203, 31, v202
	v_lshl_add_u64 v[128:129], v[202:203], 3, s[18:19]
	global_load_dwordx2 v[128:129], v[128:129], off
	v_or_b32_e32 v200, 16, v202
	v_or_b32_e32 v198, 32, v202
	v_ashrrev_i32_e32 v201, 31, v200
	v_ashrrev_i32_e32 v199, 31, v198
	v_lshl_add_u64 v[130:131], v[200:201], 3, s[18:19]
	v_lshl_add_u64 v[132:133], v[198:199], 3, s[18:19]
	global_load_dwordx2 v[130:131], v[130:131], off
	s_nop 0
	global_load_dwordx2 v[132:133], v[132:133], off
	v_or_b32_e32 v196, 48, v202
	v_add_u32_e32 v194, 0x80, v202
	v_ashrrev_i32_e32 v197, 31, v196
	v_ashrrev_i32_e32 v195, 31, v194
	v_lshl_add_u64 v[134:135], v[196:197], 3, s[18:19]
	v_lshl_add_u64 v[136:137], v[194:195], 3, s[18:19]
	global_load_dwordx2 v[134:135], v[134:135], off
	s_nop 0
	global_load_dwordx2 v[136:137], v[136:137], off
	v_add_u32_e32 v192, 0x90, v202
	v_ashrrev_i32_e32 v193, 31, v192
	v_add_u32_e32 v206, 0xa0, v202
	v_ashrrev_i32_e32 v207, 31, v206
	v_add_u32_e32 v204, 0xb0, v202
	v_ashrrev_i32_e32 v205, 31, v204
	v_lshl_or_b32 v208, s61, 8, v181
	v_ashrrev_i32_e32 v209, 31, v208
	v_lshl_add_u64 v[248:249], v[192:193], 3, s[18:19]
	global_load_dwordx2 v[248:249], v[248:249], off
	v_lshl_add_u64 v[246:247], v[206:207], 3, s[18:19]
	global_load_dwordx2 v[246:247], v[246:247], off
	v_lshl_add_u64 v[244:245], v[204:205], 3, s[18:19]
	global_load_dwordx2 v[244:245], v[244:245], off
	s_waitcnt vmcnt(0)
	v_pk_mul_f32 v[166:167], v[128:129], s[34:35] op_sel_hi:[1,0]
	s_nop 0
	v_fma_f32 v128, -v166, v166, v167
	v_max_f32_e32 v128, 0, v128
	v_add_f32_e32 v128, 0x3727c5ac, v128
	v_cmp_gt_f32_e32 vcc, s58, v128
	v_pk_mul_f32 v[162:163], v[130:131], s[34:35] op_sel_hi:[1,0]
	v_pk_mul_f32 v[160:161], v[132:133], s[34:35] op_sel_hi:[1,0]
	v_fma_f32 v129, -v162, v162, v163
	v_fma_f32 v130, -v160, v160, v161
	v_max_f32_e32 v129, 0, v129
	v_mul_f32_e32 v131, 0x4f800000, v128
	v_max_f32_e32 v130, 0, v130
	v_add_f32_e32 v129, 0x3727c5ac, v129
	v_cndmask_b32_e32 v128, v128, v131, vcc
	v_add_f32_e32 v130, 0x3727c5ac, v130
	v_mul_f32_e32 v131, 0x4f800000, v129
	v_sqrt_f32_e32 v133, v128
	v_cmp_gt_f32_e64 s[0:1], s58, v129
	v_mul_f32_e32 v132, 0x4f800000, v130
	v_cmp_gt_f32_e64 s[8:9], s58, v130
	v_cndmask_b32_e64 v129, v129, v131, s[0:1]
	v_sqrt_f32_e32 v131, v129
	v_cndmask_b32_e64 v130, v130, v132, s[8:9]
	v_sqrt_f32_e32 v132, v130
	v_add_u32_e32 v138, -1, v133
	v_add_u32_e32 v139, 1, v133
	v_fma_f32 v140, -v138, v133, v128
	v_fma_f32 v141, -v139, v133, v128
	v_add_u32_e32 v142, -1, v131
	v_cmp_ge_f32_e64 s[10:11], 0, v140
	v_add_u32_e32 v164, -1, v132
	v_add_u32_e32 v143, 1, v131
	v_cndmask_b32_e64 v133, v133, v138, s[10:11]
	v_fma_f32 v138, -v142, v131, v129
	v_cmp_lt_f32_e64 s[10:11], 0, v141
	v_fma_f32 v168, -v164, v132, v130
	v_add_u32_e32 v165, 1, v132
	v_cndmask_b32_e64 v133, v133, v139, s[10:11]
	v_cmp_ge_f32_e64 s[10:11], 0, v138
	v_fma_f32 v140, -v143, v131, v129
	v_fma_f32 v169, -v165, v132, v130
	v_cndmask_b32_e64 v131, v131, v142, s[10:11]
	v_cmp_ge_f32_e64 s[10:11], 0, v168
	v_mul_f32_e32 v138, 0x37800000, v133
	v_cndmask_b32_e32 v133, v133, v138, vcc
	v_cndmask_b32_e64 v132, v132, v164, s[10:11]
	v_cmp_lt_f32_e64 s[10:11], 0, v140
	v_cmp_class_f32_e32 vcc, v128, v189
	v_pk_mul_f32 v[170:171], v[136:137], s[34:35] op_sel_hi:[1,0]
	v_cndmask_b32_e64 v131, v131, v143, s[10:11]
	v_cmp_lt_f32_e64 s[10:11], 0, v169
	v_mul_f32_e32 v138, 0x37800000, v131
	v_cndmask_b32_e32 v128, v133, v128, vcc
	v_cndmask_b32_e64 v132, v132, v165, s[10:11]
	v_cndmask_b32_e64 v131, v131, v138, s[0:1]
	v_div_scale_f32 v133, s[0:1], v128, v128, 1.0
	v_mul_f32_e32 v139, 0x37800000, v132
	v_cmp_class_f32_e64 s[0:1], v129, v189
	v_cndmask_b32_e64 v132, v132, v139, s[8:9]
	v_div_scale_f32 v138, vcc, 1.0, v128, 1.0
	v_cndmask_b32_e64 v129, v131, v129, s[0:1]
	v_cmp_class_f32_e64 s[0:1], v130, v189
	v_rcp_f32_e32 v131, v133
	s_nop 0
	v_cndmask_b32_e64 v130, v132, v130, s[0:1]
	v_div_scale_f32 v132, s[0:1], v129, v129, 1.0
	v_div_scale_f32 v140, s[8:9], v130, v130, 1.0
	v_rcp_f32_e32 v141, v132
	v_rcp_f32_e32 v142, v140
	v_fma_f32 v143, -v133, v131, 1.0
	v_fmac_f32_e32 v131, v143, v131
	v_fma_f32 v143, -v132, v141, 1.0
	v_div_scale_f32 v139, s[0:1], 1.0, v129, 1.0
	v_fma_f32 v164, -v140, v142, 1.0
	v_mul_f32_e32 v165, v138, v131
	v_fmac_f32_e32 v141, v143, v141
	v_fmac_f32_e32 v142, v164, v142
	v_fma_f32 v143, -v133, v165, v138
	v_mul_f32_e32 v164, v139, v141
	v_fmac_f32_e32 v165, v143, v131
	v_fma_f32 v143, -v132, v164, v139
	v_fma_f32 v133, -v133, v165, v138
	v_fmac_f32_e32 v164, v143, v141
	v_div_fmas_f32 v131, v133, v131, v165
	v_fma_f32 v132, -v132, v164, v139
	s_mov_b64 vcc, s[0:1]
	v_div_fixup_f32 v184, v131, v128, 1.0
	v_div_fmas_f32 v128, v132, v141, v164
	v_div_fixup_f32 v176, v128, v129, 1.0
	v_lshl_add_u64 v[128:129], v[192:193], 3, s[18:19]
	s_nop 0
	v_pk_mul_f32 v[164:165], v[134:135], s[34:35] op_sel_hi:[1,0]
	v_div_scale_f32 v131, vcc, 1.0, v130, 1.0
	v_fma_f32 v133, -v164, v164, v165
	v_max_f32_e32 v133, 0, v133
	v_add_f32_e32 v133, 0x3727c5ac, v133
	v_mul_f32_e32 v134, 0x4f800000, v133
	v_cmp_gt_f32_e64 s[0:1], s58, v133
	v_mul_f32_e32 v132, v131, v142
	v_fma_f32 v135, -v140, v132, v131
	v_cndmask_b32_e64 v133, v133, v134, s[0:1]
	v_sqrt_f32_e32 v134, v133
	v_fmac_f32_e32 v132, v135, v142
	v_fma_f32 v131, -v140, v132, v131
	v_div_fmas_f32 v131, v131, v142, v132
	v_add_u32_e32 v135, -1, v134
	v_fma_f32 v138, -v135, v134, v133
	v_cmp_ge_f32_e64 s[8:9], 0, v138
	v_add_u32_e32 v138, 1, v134
	v_div_fixup_f32 v174, v131, v130, 1.0
	v_cndmask_b32_e64 v135, v134, v135, s[8:9]
	v_fma_f32 v134, -v138, v134, v133
	v_cmp_lt_f32_e64 s[8:9], 0, v134
	s_nop 1
	v_cndmask_b32_e64 v134, v135, v138, s[8:9]
	v_mul_f32_e32 v135, 0x37800000, v134
	v_cndmask_b32_e64 v134, v134, v135, s[0:1]
	v_cmp_class_f32_e64 s[0:1], v133, v189
	s_nop 1
	v_cndmask_b32_e64 v133, v134, v133, s[0:1]
	v_div_scale_f32 v134, s[0:1], v133, v133, 1.0
	v_rcp_f32_e32 v135, v134
	v_div_scale_f32 v132, vcc, 1.0, v133, 1.0
	v_fma_f32 v130, -v134, v135, 1.0
	v_fmac_f32_e32 v135, v130, v135
	v_lshl_add_u64 v[130:131], v[206:207], 3, s[18:19]
	s_nop 0
	v_lshl_add_u64 v[130:131], v[204:205], 3, s[18:19]
	s_nop 0
	v_fma_f32 v130, -v170, v170, v171
	v_max_f32_e32 v130, 0, v130
	v_add_f32_e32 v130, 0x3727c5ac, v130
	v_mul_f32_e32 v131, 0x4f800000, v130
	v_cmp_gt_f32_e64 s[0:1], s58, v130
	v_mul_f32_e32 v138, v132, v135
	v_fma_f32 v136, -v134, v138, v132
	v_cndmask_b32_e64 v130, v130, v131, s[0:1]
	v_sqrt_f32_e32 v131, v130
	v_fmac_f32_e32 v138, v136, v135
	v_fma_f32 v132, -v134, v138, v132
	v_div_fmas_f32 v132, v132, v135, v138
	v_add_u32_e32 v134, -1, v131
	v_fma_f32 v136, -v134, v131, v130
	v_cmp_ge_f32_e64 s[8:9], 0, v136
	v_add_u32_e32 v136, 1, v131
	v_div_fixup_f32 v186, v132, v133, 1.0
	v_cndmask_b32_e64 v134, v131, v134, s[8:9]
	v_fma_f32 v131, -v136, v131, v130
	v_cmp_lt_f32_e64 s[8:9], 0, v131
	s_nop 0
	v_pk_mul_f32 v[168:169], v[248:249], s[34:35] op_sel_hi:[1,0]
	v_cndmask_b32_e64 v131, v134, v136, s[8:9]
	v_mul_f32_e32 v134, 0x37800000, v131
	v_cndmask_b32_e64 v131, v131, v134, s[0:1]
	v_cmp_class_f32_e64 s[0:1], v130, v189
	v_fma_f32 v128, -v168, v168, v169
	v_max_f32_e32 v128, 0, v128
	v_cndmask_b32_e64 v130, v131, v130, s[0:1]
	v_div_scale_f32 v131, s[0:1], v130, v130, 1.0
	v_rcp_f32_e32 v134, v131
	v_add_f32_e32 v128, 0x3727c5ac, v128
	v_mul_f32_e32 v129, 0x4f800000, v128
	v_cmp_gt_f32_e64 s[0:1], s58, v128
	v_fma_f32 v132, -v131, v134, 1.0
	v_fmac_f32_e32 v134, v132, v134
	v_cndmask_b32_e64 v128, v128, v129, s[0:1]
	v_div_scale_f32 v132, vcc, 1.0, v130, 1.0
	v_sqrt_f32_e32 v129, v128
	v_mul_f32_e32 v133, v132, v134
	v_fma_f32 v135, -v131, v133, v132
	v_fmac_f32_e32 v133, v135, v134
	v_fma_f32 v131, -v131, v133, v132
	v_add_u32_e32 v132, -1, v129
	v_fma_f32 v135, -v132, v129, v128
	v_cmp_ge_f32_e64 s[8:9], 0, v135
	v_add_u32_e32 v135, 1, v129
	v_pk_mul_f32 v[178:179], v[246:247], s[34:35] op_sel_hi:[1,0]
	v_cndmask_b32_e64 v132, v129, v132, s[8:9]
	v_fma_f32 v129, -v135, v129, v128
	v_cmp_lt_f32_e64 s[8:9], 0, v129
	v_fma_f32 v172, -v178, v178, v179
	v_max_f32_e32 v172, 0, v172
	v_cndmask_b32_e64 v129, v132, v135, s[8:9]
	v_mul_f32_e32 v132, 0x37800000, v129
	v_cndmask_b32_e64 v129, v129, v132, s[0:1]
	v_cmp_class_f32_e64 s[0:1], v128, v189
	v_add_f32_e32 v172, 0x3727c5ac, v172
	v_mul_f32_e32 v173, 0x4f800000, v172
	v_cndmask_b32_e64 v180, v129, v128, s[0:1]
	v_div_scale_f32 v188, s[0:1], v180, v180, 1.0
	v_rcp_f32_e32 v190, v188
	v_div_fmas_f32 v128, v131, v134, v133
	v_lshlrev_b64 v[132:133], 2, v[208:209]
	v_div_fixup_f32 v182, v128, v130, 1.0
	v_fma_f32 v128, -v188, v190, 1.0
	v_lshl_add_u64 v[134:135], s[22:23], 0, v[132:133]
	v_fmac_f32_e32 v190, v128, v190
	global_load_dwordx4 v[128:131], v[134:135], off offset:16
	global_load_dwordx4 v[140:143], v[134:135], off
	v_lshl_add_u64 v[136:137], s[24:25], 0, v[132:133]
	global_load_dwordx4 v[132:135], v[136:137], off offset:16
	s_nop 0
	global_load_dwordx4 v[136:139], v[136:137], off
	v_cmp_gt_f32_e64 s[0:1], s58, v172
	v_div_scale_f32 v191, vcc, 1.0, v180, 1.0
	s_nop 0
	v_cndmask_b32_e64 v172, v172, v173, s[0:1]
	v_sqrt_f32_e32 v173, v172
	v_mul_f32_e32 v212, v191, v190
	v_fma_f32 v213, -v188, v212, v191
	v_fmac_f32_e32 v212, v213, v190
	v_fma_f32 v188, -v188, v212, v191
	v_add_u32_e32 v191, -1, v173
	v_fma_f32 v213, -v191, v173, v172
	v_cmp_ge_f32_e64 s[8:9], 0, v213
	v_add_u32_e32 v213, 1, v173
	s_waitcnt vmcnt(0)
	v_pk_fma_f32 v[120:121], v[166:167], v[128:129], v[120:121] op_sel_hi:[0,1,1] neg_lo:[1,0,0] neg_hi:[1,0,0]
	v_cndmask_b32_e64 v191, v173, v191, s[8:9]
	v_fma_f32 v173, -v213, v173, v172
	v_cmp_lt_f32_e64 s[8:9], 0, v173
	v_pk_fma_f32 v[124:125], v[166:167], v[140:141], v[124:125] op_sel_hi:[0,1,1] neg_lo:[1,0,0] neg_hi:[1,0,0]
	v_pk_fma_f32 v[126:127], v[166:167], v[142:143], v[126:127] op_sel_hi:[0,1,1] neg_lo:[1,0,0] neg_hi:[1,0,0]
	v_cndmask_b32_e64 v173, v191, v213, s[8:9]
	v_mul_f32_e32 v191, 0x37800000, v173
	v_cndmask_b32_e64 v173, v173, v191, s[0:1]
	v_cmp_class_f32_e64 s[0:1], v172, v189
	v_pk_fma_f32 v[126:127], v[184:185], v[126:127], v[138:139] op_sel_hi:[0,1,1]
	v_pk_fma_f32 v[124:125], v[184:185], v[124:125], v[136:137] op_sel_hi:[0,1,1]
	v_cndmask_b32_e64 v191, v173, v172, s[0:1]
	v_div_scale_f32 v213, s[0:1], v191, v191, 1.0
	v_rcp_f32_e32 v214, v213
	v_div_fmas_f32 v172, v188, v190, v212
	v_div_fixup_f32 v190, v172, v180, 1.0
	v_div_scale_f32 v180, vcc, 1.0, v191, 1.0
	v_fma_f32 v172, -v213, v214, 1.0
	v_fmac_f32_e32 v214, v172, v214
	v_pk_mul_f32 v[172:173], v[244:245], s[34:35] op_sel_hi:[1,0]
	v_mul_f32_e32 v188, v180, v214
	v_fma_f32 v210, -v172, v172, v173
	v_max_f32_e32 v210, 0, v210
	v_add_f32_e32 v210, 0x3727c5ac, v210
	v_mul_f32_e32 v211, 0x4f800000, v210
	v_cmp_gt_f32_e64 s[0:1], s58, v210
	v_fma_f32 v212, -v213, v188, v180
	v_fmac_f32_e32 v188, v212, v214
	v_cndmask_b32_e64 v210, v210, v211, s[0:1]
	v_sqrt_f32_e32 v211, v210
	v_fma_f32 v180, -v213, v188, v180
	v_pk_fma_f32 v[122:123], v[166:167], v[130:131], v[122:123] op_sel_hi:[0,1,1] neg_lo:[1,0,0] neg_hi:[1,0,0]
	v_pk_fma_f32 v[120:121], v[184:185], v[120:121], v[132:133] op_sel_hi:[0,1,1]
	v_add_u32_e32 v212, -1, v211
	v_fma_f32 v213, -v212, v211, v210
	v_cmp_ge_f32_e64 s[8:9], 0, v213
	v_add_u32_e32 v213, 1, v211
	v_pk_fma_f32 v[122:123], v[184:185], v[122:123], v[134:135] op_sel_hi:[0,1,1]
	v_cndmask_b32_e64 v212, v211, v212, s[8:9]
	v_fma_f32 v211, -v213, v211, v210
	v_cmp_lt_f32_e64 s[8:9], 0, v211
	v_max_f32_e32 v124, 0, v124
	v_max_f32_e32 v120, 0, v120
	v_cndmask_b32_e64 v211, v212, v213, s[8:9]
	v_max_f32_e32 v125, 0, v125
	v_max_f32_e32 v121, 0, v121
	v_max_f32_e32 v126, 0, v126
	v_max_f32_e32 v127, 0, v127
	v_mul_f32_e32 v212, 0x37800000, v211
	v_pk_mul_f32 v[124:125], v[124:125], v[124:125]
	v_pk_mul_f32 v[120:121], v[120:121], v[120:121]
	v_max_f32_e32 v122, 0, v122
	v_max_f32_e32 v123, 0, v123
	v_pk_mul_f32 v[126:127], v[126:127], v[126:127]
	v_pk_fma_f32 v[116:117], v[162:163], v[140:141], v[116:117] op_sel_hi:[0,1,1] neg_lo:[1,0,0] neg_hi:[1,0,0]
	v_pk_fma_f32 v[112:113], v[162:163], v[128:129], v[112:113] op_sel_hi:[0,1,1] neg_lo:[1,0,0] neg_hi:[1,0,0]
	v_cndmask_b32_e64 v211, v211, v212, s[0:1]
	v_cmp_class_f32_e64 s[0:1], v210, v189
	v_pk_mul_f32 v[122:123], v[122:123], v[122:123]
	v_cvt_pk_bf16_f32 v124, v124, v125
	v_cvt_pk_bf16_f32 v125, v126, v127
	v_cvt_pk_bf16_f32 v126, v120, v121
	v_lshlrev_b64 v[120:121], 14, v[202:203]
	v_pk_fma_f32 v[116:117], v[176:177], v[116:117], v[136:137] op_sel_hi:[0,1,1]
	v_pk_fma_f32 v[114:115], v[162:163], v[130:131], v[114:115] op_sel_hi:[0,1,1] neg_lo:[1,0,0] neg_hi:[1,0,0]
	v_pk_fma_f32 v[112:113], v[176:177], v[112:113], v[132:133] op_sel_hi:[0,1,1]
	v_cndmask_b32_e64 v210, v211, v210, s[0:1]
	v_cvt_pk_bf16_f32 v127, v122, v123
	v_lshl_add_u64 v[120:121], s[50:51], 0, v[120:121]
	v_lshlrev_b64 v[122:123], 1, v[208:209]
	v_pk_fma_f32 v[118:119], v[162:163], v[142:143], v[118:119] op_sel_hi:[0,1,1] neg_lo:[1,0,0] neg_hi:[1,0,0]
	v_pk_fma_f32 v[114:115], v[176:177], v[114:115], v[134:135] op_sel_hi:[0,1,1]
	v_max_f32_e32 v116, 0, v116
	v_max_f32_e32 v112, 0, v112
	v_max_f32_e32 v117, 0, v117
	v_max_f32_e32 v113, 0, v113
	v_div_scale_f32 v211, s[0:1], v210, v210, 1.0
	v_lshl_add_u64 v[120:121], v[120:121], 0, v[122:123]
	v_pk_fma_f32 v[118:119], v[176:177], v[118:119], v[138:139] op_sel_hi:[0,1,1]
	v_pk_mul_f32 v[116:117], v[116:117], v[116:117]
	v_pk_mul_f32 v[112:113], v[112:113], v[112:113]
	v_max_f32_e32 v114, 0, v114
	v_max_f32_e32 v115, 0, v115
	v_pk_fma_f32 v[108:109], v[160:161], v[140:141], v[108:109] op_sel_hi:[0,1,1] neg_lo:[1,0,0] neg_hi:[1,0,0]
	v_pk_fma_f32 v[104:105], v[160:161], v[128:129], v[104:105] op_sel_hi:[0,1,1] neg_lo:[1,0,0] neg_hi:[1,0,0]
	v_rcp_f32_e32 v212, v211
	global_store_dwordx4 v[120:121], v[124:127], off
	v_max_f32_e32 v118, 0, v118
	v_max_f32_e32 v119, 0, v119
	v_pk_mul_f32 v[124:125], v[114:115], v[114:115]
	v_cvt_pk_bf16_f32 v114, v116, v117
	v_cvt_pk_bf16_f32 v116, v112, v113
	v_lshlrev_b64 v[112:113], 14, v[200:201]
	v_pk_fma_f32 v[108:109], v[174:175], v[108:109], v[136:137] op_sel_hi:[0,1,1]
	v_pk_fma_f32 v[106:107], v[160:161], v[130:131], v[106:107] op_sel_hi:[0,1,1] neg_lo:[1,0,0] neg_hi:[1,0,0]
	v_pk_fma_f32 v[104:105], v[174:175], v[104:105], v[132:133] op_sel_hi:[0,1,1]
	v_pk_mul_f32 v[118:119], v[118:119], v[118:119]
	v_lshl_add_u64 v[112:113], s[50:51], 0, v[112:113]
	v_pk_fma_f32 v[110:111], v[160:161], v[142:143], v[110:111] op_sel_hi:[0,1,1] neg_lo:[1,0,0] neg_hi:[1,0,0]
	v_pk_fma_f32 v[106:107], v[174:175], v[106:107], v[134:135] op_sel_hi:[0,1,1]
	v_max_f32_e32 v108, 0, v108
	v_max_f32_e32 v104, 0, v104
	v_max_f32_e32 v109, 0, v109
	v_max_f32_e32 v105, 0, v105
	v_cvt_pk_bf16_f32 v115, v118, v119
	v_cvt_pk_bf16_f32 v117, v124, v125
	v_lshl_add_u64 v[112:113], v[112:113], 0, v[122:123]
	v_pk_fma_f32 v[110:111], v[174:175], v[110:111], v[138:139] op_sel_hi:[0,1,1]
	v_pk_mul_f32 v[108:109], v[108:109], v[108:109]
	v_pk_mul_f32 v[104:105], v[104:105], v[104:105]
	v_max_f32_e32 v106, 0, v106
	v_max_f32_e32 v107, 0, v107
	v_pk_fma_f32 v[100:101], v[164:165], v[140:141], v[100:101] op_sel_hi:[0,1,1] neg_lo:[1,0,0] neg_hi:[1,0,0]
	v_pk_fma_f32 v[96:97], v[164:165], v[128:129], v[96:97] op_sel_hi:[0,1,1] neg_lo:[1,0,0] neg_hi:[1,0,0]
	v_div_fmas_f32 v180, v180, v214, v188
	global_store_dwordx4 v[112:113], v[114:117], off
	v_max_f32_e32 v110, 0, v110
	v_max_f32_e32 v111, 0, v111
	v_pk_mul_f32 v[114:115], v[106:107], v[106:107]
	v_cvt_pk_bf16_f32 v106, v108, v109
	v_cvt_pk_bf16_f32 v108, v104, v105
	v_lshlrev_b64 v[104:105], 14, v[198:199]
	v_pk_fma_f32 v[100:101], v[186:187], v[100:101], v[136:137] op_sel_hi:[0,1,1]
	v_pk_fma_f32 v[98:99], v[164:165], v[130:131], v[98:99] op_sel_hi:[0,1,1] neg_lo:[1,0,0] neg_hi:[1,0,0]
	v_pk_fma_f32 v[96:97], v[186:187], v[96:97], v[132:133] op_sel_hi:[0,1,1]
	v_div_fixup_f32 v188, v180, v191, 1.0
	v_fma_f32 v180, -v211, v212, 1.0
	v_pk_mul_f32 v[110:111], v[110:111], v[110:111]
	v_lshl_add_u64 v[104:105], s[50:51], 0, v[104:105]
	v_pk_fma_f32 v[102:103], v[164:165], v[142:143], v[102:103] op_sel_hi:[0,1,1] neg_lo:[1,0,0] neg_hi:[1,0,0]
	v_pk_fma_f32 v[98:99], v[186:187], v[98:99], v[134:135] op_sel_hi:[0,1,1]
	v_max_f32_e32 v100, 0, v100
	v_max_f32_e32 v96, 0, v96
	v_max_f32_e32 v101, 0, v101
	v_max_f32_e32 v97, 0, v97
	v_fmac_f32_e32 v212, v180, v212
	v_div_scale_f32 v180, vcc, 1.0, v210, 1.0
	v_cvt_pk_bf16_f32 v107, v110, v111
	v_cvt_pk_bf16_f32 v109, v114, v115
	v_lshl_add_u64 v[104:105], v[104:105], 0, v[122:123]
	v_pk_fma_f32 v[102:103], v[186:187], v[102:103], v[138:139] op_sel_hi:[0,1,1]
	v_pk_mul_f32 v[100:101], v[100:101], v[100:101]
	v_pk_mul_f32 v[96:97], v[96:97], v[96:97]
	v_max_f32_e32 v98, 0, v98
	v_max_f32_e32 v99, 0, v99
	v_pk_fma_f32 v[92:93], v[170:171], v[140:141], v[92:93] op_sel_hi:[0,1,1] neg_lo:[1,0,0] neg_hi:[1,0,0]
	v_pk_fma_f32 v[88:89], v[170:171], v[128:129], v[88:89] op_sel_hi:[0,1,1] neg_lo:[1,0,0] neg_hi:[1,0,0]
	v_mul_f32_e32 v191, v180, v212
	global_store_dwordx4 v[104:105], v[106:109], off
	v_max_f32_e32 v102, 0, v102
	v_max_f32_e32 v103, 0, v103
	v_pk_mul_f32 v[106:107], v[98:99], v[98:99]
	v_cvt_pk_bf16_f32 v98, v100, v101
	v_cvt_pk_bf16_f32 v100, v96, v97
	v_lshlrev_b64 v[96:97], 14, v[196:197]
	v_pk_fma_f32 v[92:93], v[182:183], v[92:93], v[136:137] op_sel_hi:[0,1,1]
	v_pk_fma_f32 v[90:91], v[170:171], v[130:131], v[90:91] op_sel_hi:[0,1,1] neg_lo:[1,0,0] neg_hi:[1,0,0]
	v_pk_fma_f32 v[88:89], v[182:183], v[88:89], v[132:133] op_sel_hi:[0,1,1]
	v_fma_f32 v213, -v211, v191, v180
	v_pk_mul_f32 v[102:103], v[102:103], v[102:103]
	v_lshl_add_u64 v[96:97], s[50:51], 0, v[96:97]
	v_pk_fma_f32 v[94:95], v[170:171], v[142:143], v[94:95] op_sel_hi:[0,1,1] neg_lo:[1,0,0] neg_hi:[1,0,0]
	v_pk_fma_f32 v[90:91], v[182:183], v[90:91], v[134:135] op_sel_hi:[0,1,1]
	v_max_f32_e32 v92, 0, v92
	v_max_f32_e32 v88, 0, v88
	v_max_f32_e32 v93, 0, v93
	v_max_f32_e32 v89, 0, v89
	v_fmac_f32_e32 v191, v213, v212
	v_cvt_pk_bf16_f32 v99, v102, v103
	v_cvt_pk_bf16_f32 v101, v106, v107
	v_lshl_add_u64 v[96:97], v[96:97], 0, v[122:123]
	v_pk_fma_f32 v[94:95], v[182:183], v[94:95], v[138:139] op_sel_hi:[0,1,1]
	v_pk_mul_f32 v[92:93], v[92:93], v[92:93]
	v_pk_mul_f32 v[88:89], v[88:89], v[88:89]
	v_max_f32_e32 v90, 0, v90
	v_max_f32_e32 v91, 0, v91
	v_pk_fma_f32 v[84:85], v[168:169], v[140:141], v[84:85] op_sel_hi:[0,1,1] neg_lo:[1,0,0] neg_hi:[1,0,0]
	v_pk_fma_f32 v[80:81], v[168:169], v[128:129], v[80:81] op_sel_hi:[0,1,1] neg_lo:[1,0,0] neg_hi:[1,0,0]
	global_store_dwordx4 v[96:97], v[98:101], off
	v_max_f32_e32 v94, 0, v94
	v_max_f32_e32 v95, 0, v95
	v_pk_mul_f32 v[98:99], v[90:91], v[90:91]
	v_cvt_pk_bf16_f32 v90, v92, v93
	v_cvt_pk_bf16_f32 v92, v88, v89
	v_lshlrev_b64 v[88:89], 14, v[194:195]
	v_pk_fma_f32 v[84:85], v[84:85], v[190:191], v[136:137] op_sel_hi:[1,0,1]
	v_pk_fma_f32 v[82:83], v[168:169], v[130:131], v[82:83] op_sel_hi:[0,1,1] neg_lo:[1,0,0] neg_hi:[1,0,0]
	v_pk_fma_f32 v[80:81], v[190:191], v[80:81], v[132:133] op_sel_hi:[0,1,1]
	v_pk_mul_f32 v[94:95], v[94:95], v[94:95]
	v_lshl_add_u64 v[88:89], s[50:51], 0, v[88:89]
	v_pk_fma_f32 v[86:87], v[168:169], v[142:143], v[86:87] op_sel_hi:[0,1,1] neg_lo:[1,0,0] neg_hi:[1,0,0]
	v_pk_fma_f32 v[82:83], v[190:191], v[82:83], v[134:135] op_sel_hi:[0,1,1]
	v_max_f32_e32 v84, 0, v84
	v_max_f32_e32 v80, 0, v80
	v_max_f32_e32 v85, 0, v85
	v_max_f32_e32 v81, 0, v81
	v_cvt_pk_bf16_f32 v91, v94, v95
	v_cvt_pk_bf16_f32 v93, v98, v99
	v_lshl_add_u64 v[88:89], v[88:89], 0, v[122:123]
	v_pk_fma_f32 v[86:87], v[86:87], v[190:191], v[138:139] op_sel_hi:[1,0,1]
	v_pk_mul_f32 v[84:85], v[84:85], v[84:85]
	v_pk_mul_f32 v[80:81], v[80:81], v[80:81]
	v_max_f32_e32 v82, 0, v82
	v_max_f32_e32 v83, 0, v83
	global_store_dwordx4 v[88:89], v[90:93], off
	v_max_f32_e32 v86, 0, v86
	v_max_f32_e32 v87, 0, v87
	v_pk_mul_f32 v[90:91], v[82:83], v[82:83]
	v_cvt_pk_bf16_f32 v82, v84, v85
	v_cvt_pk_bf16_f32 v84, v80, v81
	v_lshlrev_b64 v[80:81], 14, v[192:193]
	v_pk_fma_f32 v[76:77], v[178:179], v[140:141], v[76:77] op_sel_hi:[0,1,1] neg_lo:[1,0,0] neg_hi:[1,0,0]
	v_pk_fma_f32 v[72:73], v[178:179], v[128:129], v[72:73] op_sel_hi:[0,1,1] neg_lo:[1,0,0] neg_hi:[1,0,0]
	v_pk_mul_f32 v[86:87], v[86:87], v[86:87]
	v_lshl_add_u64 v[80:81], s[50:51], 0, v[80:81]
	v_pk_fma_f32 v[78:79], v[178:179], v[142:143], v[78:79] op_sel_hi:[0,1,1] neg_lo:[1,0,0] neg_hi:[1,0,0]
	v_pk_fma_f32 v[76:77], v[76:77], v[188:189], v[136:137] op_sel_hi:[1,0,1]
	v_pk_fma_f32 v[72:73], v[72:73], v[188:189], v[132:133] op_sel_hi:[1,0,1]
	v_cvt_pk_bf16_f32 v83, v86, v87
	v_cvt_pk_bf16_f32 v85, v90, v91
	v_lshl_add_u64 v[80:81], v[80:81], 0, v[122:123]
	v_pk_fma_f32 v[78:79], v[78:79], v[188:189], v[138:139] op_sel_hi:[1,0,1]
	v_pk_fma_f32 v[74:75], v[178:179], v[130:131], v[74:75] op_sel_hi:[0,1,1] neg_lo:[1,0,0] neg_hi:[1,0,0]
	v_max_f32_e32 v76, 0, v76
	v_max_f32_e32 v72, 0, v72
	v_max_f32_e32 v77, 0, v77
	v_max_f32_e32 v73, 0, v73
	global_store_dwordx4 v[80:81], v[82:85], off
	v_pk_fma_f32 v[74:75], v[74:75], v[188:189], v[134:135] op_sel_hi:[1,0,1]
	v_pk_mul_f32 v[76:77], v[76:77], v[76:77]
	v_pk_mul_f32 v[82:83], v[72:73], v[72:73]
	v_max_f32_e32 v72, 0, v78
	v_max_f32_e32 v73, 0, v79
	v_max_f32_e32 v74, 0, v74
	v_max_f32_e32 v75, 0, v75
	v_pk_mul_f32 v[78:79], v[72:73], v[72:73]
	v_cvt_pk_bf16_f32 v72, v76, v77
	v_lshlrev_b64 v[76:77], 14, v[206:207]
	v_fma_f32 v180, -v211, v191, v180
	v_pk_mul_f32 v[84:85], v[74:75], v[74:75]
	v_lshl_add_u64 v[76:77], s[50:51], 0, v[76:77]
	v_div_fmas_f32 v180, v180, v212, v191
	v_cvt_pk_bf16_f32 v73, v78, v79
	v_cvt_pk_bf16_f32 v74, v82, v83
	v_cvt_pk_bf16_f32 v75, v84, v85
	v_lshl_add_u64 v[82:83], v[76:77], 0, v[122:123]
	v_div_fixup_f32 v180, v180, v210, 1.0
	global_store_dwordx4 v[82:83], v[72:75], off
	v_pk_fma_f32 v[68:69], v[140:141], v[172:173], v[68:69] op_sel_hi:[1,0,1] neg_lo:[1,0,0] neg_hi:[1,0,0]
	v_pk_fma_f32 v[64:65], v[172:173], v[128:129], v[64:65] op_sel_hi:[0,1,1] neg_lo:[1,0,0] neg_hi:[1,0,0]
	v_xor_b32_e32 v73, 0x80000000, v143
	v_xor_b32_e32 v72, 0x80000000, v142
	v_pk_fma_f32 v[70:71], v[72:73], v[172:173], v[70:71] op_sel_hi:[1,0,1]
	v_pk_fma_f32 v[68:69], v[68:69], v[180:181], v[136:137] op_sel_hi:[1,0,1]
	v_pk_fma_f32 v[64:65], v[64:65], v[180:181], v[132:133] op_sel_hi:[1,0,1]
	v_pk_fma_f32 v[70:71], v[70:71], v[180:181], v[138:139] op_sel_hi:[1,0,1]
	v_pk_fma_f32 v[66:67], v[172:173], v[130:131], v[66:67] op_sel_hi:[0,1,1] neg_lo:[1,0,0] neg_hi:[1,0,0]
	v_max_f32_e32 v68, 0, v68
	v_max_f32_e32 v64, 0, v64
	v_max_f32_e32 v69, 0, v69
	v_max_f32_e32 v65, 0, v65
	v_pk_fma_f32 v[66:67], v[66:67], v[180:181], v[134:135] op_sel_hi:[1,0,1]
	v_pk_mul_f32 v[68:69], v[68:69], v[68:69]
	v_pk_mul_f32 v[72:73], v[64:65], v[64:65]
	v_max_f32_e32 v64, 0, v70
	v_max_f32_e32 v65, 0, v71
	v_max_f32_e32 v66, 0, v66
	v_max_f32_e32 v67, 0, v67
	v_pk_mul_f32 v[70:71], v[64:65], v[64:65]
	v_cvt_pk_bf16_f32 v64, v68, v69
	v_lshlrev_b64 v[68:69], 14, v[204:205]
	v_pk_mul_f32 v[74:75], v[66:67], v[66:67]
	v_lshl_add_u64 v[68:69], s[50:51], 0, v[68:69]
	v_cvt_pk_bf16_f32 v65, v70, v71
	v_cvt_pk_bf16_f32 v66, v72, v73
	v_cvt_pk_bf16_f32 v67, v74, v75
	v_lshl_add_u64 v[84:85], v[68:69], 0, v[122:123]
	global_store_dwordx4 v[84:85], v[64:67], off
	s_and_b64 vcc, exec, s[6:7]
	s_mov_b64 s[0:1], -1
	v_or_b32_e32 v64, 0x80, v208
	v_ashrrev_i32_e32 v65, 31, v64
	v_lshlrev_b64 v[64:65], 2, v[64:65]
	v_lshl_add_u64 v[66:67], s[22:23], 0, v[64:65]
	v_lshl_add_u64 v[64:65], s[24:25], 0, v[64:65]
	global_load_dwordx4 v[72:75], v[66:67], off
	global_load_dwordx4 v[76:79], v[64:65], off
	global_load_dwordx4 v[68:71], v[66:67], off offset:16
	s_nop 0
	global_load_dwordx4 v[64:67], v[64:65], off offset:16
	s_waitcnt vmcnt(0)
	v_pk_fma_f32 v[56:57], v[166:167], v[68:69], v[56:57] op_sel_hi:[0,1,1] neg_lo:[1,0,0] neg_hi:[1,0,0]
	v_pk_fma_f32 v[60:61], v[166:167], v[72:73], v[60:61] op_sel_hi:[0,1,1] neg_lo:[1,0,0] neg_hi:[1,0,0]
	v_pk_fma_f32 v[62:63], v[166:167], v[74:75], v[62:63] op_sel_hi:[0,1,1] neg_lo:[1,0,0] neg_hi:[1,0,0]
	v_pk_fma_f32 v[58:59], v[166:167], v[70:71], v[58:59] op_sel_hi:[0,1,1] neg_lo:[1,0,0] neg_hi:[1,0,0]
	v_pk_fma_f32 v[56:57], v[184:185], v[56:57], v[64:65] op_sel_hi:[0,1,1]
	v_pk_fma_f32 v[62:63], v[184:185], v[62:63], v[78:79] op_sel_hi:[0,1,1]
	v_pk_fma_f32 v[60:61], v[184:185], v[60:61], v[76:77] op_sel_hi:[0,1,1]
	v_pk_fma_f32 v[58:59], v[184:185], v[58:59], v[66:67] op_sel_hi:[0,1,1]
	v_max_f32_e32 v56, 0, v56
	v_max_f32_e32 v57, 0, v57
	v_max_f32_e32 v60, 0, v60
	v_max_f32_e32 v61, 0, v61
	v_pk_mul_f32 v[86:87], v[56:57], v[56:57]
	v_max_f32_e32 v56, 0, v62
	v_max_f32_e32 v58, 0, v58
	v_max_f32_e32 v57, 0, v63
	v_max_f32_e32 v59, 0, v59
	v_pk_fma_f32 v[48:49], v[162:163], v[68:69], v[48:49] op_sel_hi:[0,1,1] neg_lo:[1,0,0] neg_hi:[1,0,0]
	v_pk_mul_f32 v[60:61], v[60:61], v[60:61]
	v_pk_mul_f32 v[62:63], v[56:57], v[56:57]
	v_pk_mul_f32 v[90:91], v[58:59], v[58:59]
	v_pk_fma_f32 v[52:53], v[162:163], v[72:73], v[52:53] op_sel_hi:[0,1,1] neg_lo:[1,0,0] neg_hi:[1,0,0]
	v_pk_fma_f32 v[54:55], v[162:163], v[74:75], v[54:55] op_sel_hi:[0,1,1] neg_lo:[1,0,0] neg_hi:[1,0,0]
	v_pk_fma_f32 v[50:51], v[162:163], v[70:71], v[50:51] op_sel_hi:[0,1,1] neg_lo:[1,0,0] neg_hi:[1,0,0]
	v_pk_fma_f32 v[48:49], v[176:177], v[48:49], v[64:65] op_sel_hi:[0,1,1]
	v_cvt_pk_bf16_f32 v56, v60, v61
	v_cvt_pk_bf16_f32 v57, v62, v63
	v_cvt_pk_bf16_f32 v58, v86, v87
	v_cvt_pk_bf16_f32 v59, v90, v91
	v_pk_fma_f32 v[54:55], v[176:177], v[54:55], v[78:79] op_sel_hi:[0,1,1]
	v_pk_fma_f32 v[52:53], v[176:177], v[52:53], v[76:77] op_sel_hi:[0,1,1]
	v_pk_fma_f32 v[50:51], v[176:177], v[50:51], v[66:67] op_sel_hi:[0,1,1]
	v_max_f32_e32 v48, 0, v48
	v_max_f32_e32 v49, 0, v49
	global_store_dwordx4 v[120:121], v[56:59], off offset:256
	v_max_f32_e32 v52, 0, v52
	v_max_f32_e32 v53, 0, v53
	v_pk_mul_f32 v[56:57], v[48:49], v[48:49]
	v_max_f32_e32 v48, 0, v54
	v_max_f32_e32 v50, 0, v50
	v_max_f32_e32 v49, 0, v55
	v_max_f32_e32 v51, 0, v51
	v_pk_fma_f32 v[40:41], v[160:161], v[68:69], v[40:41] op_sel_hi:[0,1,1] neg_lo:[1,0,0] neg_hi:[1,0,0]
	v_pk_mul_f32 v[52:53], v[52:53], v[52:53]
	v_pk_mul_f32 v[54:55], v[48:49], v[48:49]
	v_pk_mul_f32 v[58:59], v[50:51], v[50:51]
	v_pk_fma_f32 v[44:45], v[160:161], v[72:73], v[44:45] op_sel_hi:[0,1,1] neg_lo:[1,0,0] neg_hi:[1,0,0]
	v_pk_fma_f32 v[46:47], v[160:161], v[74:75], v[46:47] op_sel_hi:[0,1,1] neg_lo:[1,0,0] neg_hi:[1,0,0]
	v_pk_fma_f32 v[42:43], v[160:161], v[70:71], v[42:43] op_sel_hi:[0,1,1] neg_lo:[1,0,0] neg_hi:[1,0,0]
	v_pk_fma_f32 v[40:41], v[174:175], v[40:41], v[64:65] op_sel_hi:[0,1,1]
	v_cvt_pk_bf16_f32 v48, v52, v53
	v_cvt_pk_bf16_f32 v49, v54, v55
	v_cvt_pk_bf16_f32 v50, v56, v57
	v_cvt_pk_bf16_f32 v51, v58, v59
	v_pk_fma_f32 v[46:47], v[174:175], v[46:47], v[78:79] op_sel_hi:[0,1,1]
	v_pk_fma_f32 v[44:45], v[174:175], v[44:45], v[76:77] op_sel_hi:[0,1,1]
	v_pk_fma_f32 v[42:43], v[174:175], v[42:43], v[66:67] op_sel_hi:[0,1,1]
	v_max_f32_e32 v40, 0, v40
	v_max_f32_e32 v41, 0, v41
	global_store_dwordx4 v[112:113], v[48:51], off offset:256
	v_max_f32_e32 v44, 0, v44
	v_max_f32_e32 v45, 0, v45
	v_pk_mul_f32 v[48:49], v[40:41], v[40:41]
	v_max_f32_e32 v40, 0, v46
	v_max_f32_e32 v42, 0, v42
	v_max_f32_e32 v41, 0, v47
	v_max_f32_e32 v43, 0, v43
	v_pk_fma_f32 v[32:33], v[164:165], v[68:69], v[32:33] op_sel_hi:[0,1,1] neg_lo:[1,0,0] neg_hi:[1,0,0]
	v_pk_mul_f32 v[44:45], v[44:45], v[44:45]
	v_pk_mul_f32 v[46:47], v[40:41], v[40:41]
	v_pk_mul_f32 v[50:51], v[42:43], v[42:43]
	v_pk_fma_f32 v[36:37], v[164:165], v[72:73], v[36:37] op_sel_hi:[0,1,1] neg_lo:[1,0,0] neg_hi:[1,0,0]
	v_pk_fma_f32 v[38:39], v[164:165], v[74:75], v[38:39] op_sel_hi:[0,1,1] neg_lo:[1,0,0] neg_hi:[1,0,0]
	v_pk_fma_f32 v[34:35], v[164:165], v[70:71], v[34:35] op_sel_hi:[0,1,1] neg_lo:[1,0,0] neg_hi:[1,0,0]
	v_pk_fma_f32 v[32:33], v[186:187], v[32:33], v[64:65] op_sel_hi:[0,1,1]
	v_cvt_pk_bf16_f32 v40, v44, v45
	v_cvt_pk_bf16_f32 v41, v46, v47
	v_cvt_pk_bf16_f32 v42, v48, v49
	v_cvt_pk_bf16_f32 v43, v50, v51
	v_pk_fma_f32 v[38:39], v[186:187], v[38:39], v[78:79] op_sel_hi:[0,1,1]
	v_pk_fma_f32 v[36:37], v[186:187], v[36:37], v[76:77] op_sel_hi:[0,1,1]
	v_pk_fma_f32 v[34:35], v[186:187], v[34:35], v[66:67] op_sel_hi:[0,1,1]
	v_max_f32_e32 v32, 0, v32
	v_max_f32_e32 v33, 0, v33
	global_store_dwordx4 v[104:105], v[40:43], off offset:256
	v_max_f32_e32 v36, 0, v36
	v_max_f32_e32 v37, 0, v37
	v_pk_mul_f32 v[40:41], v[32:33], v[32:33]
	v_max_f32_e32 v32, 0, v38
	v_max_f32_e32 v34, 0, v34
	v_max_f32_e32 v33, 0, v39
	v_max_f32_e32 v35, 0, v35
	v_pk_fma_f32 v[24:25], v[170:171], v[68:69], v[24:25] op_sel_hi:[0,1,1] neg_lo:[1,0,0] neg_hi:[1,0,0]
	v_pk_mul_f32 v[36:37], v[36:37], v[36:37]
	v_pk_mul_f32 v[38:39], v[32:33], v[32:33]
	v_pk_mul_f32 v[42:43], v[34:35], v[34:35]
	v_pk_fma_f32 v[28:29], v[170:171], v[72:73], v[28:29] op_sel_hi:[0,1,1] neg_lo:[1,0,0] neg_hi:[1,0,0]
	v_pk_fma_f32 v[30:31], v[170:171], v[74:75], v[30:31] op_sel_hi:[0,1,1] neg_lo:[1,0,0] neg_hi:[1,0,0]
	v_pk_fma_f32 v[26:27], v[170:171], v[70:71], v[26:27] op_sel_hi:[0,1,1] neg_lo:[1,0,0] neg_hi:[1,0,0]
	v_pk_fma_f32 v[24:25], v[182:183], v[24:25], v[64:65] op_sel_hi:[0,1,1]
	v_cvt_pk_bf16_f32 v32, v36, v37
	v_cvt_pk_bf16_f32 v33, v38, v39
	v_cvt_pk_bf16_f32 v34, v40, v41
	v_cvt_pk_bf16_f32 v35, v42, v43
	v_pk_fma_f32 v[30:31], v[182:183], v[30:31], v[78:79] op_sel_hi:[0,1,1]
	v_pk_fma_f32 v[28:29], v[182:183], v[28:29], v[76:77] op_sel_hi:[0,1,1]
	v_pk_fma_f32 v[26:27], v[182:183], v[26:27], v[66:67] op_sel_hi:[0,1,1]
	v_max_f32_e32 v24, 0, v24
	v_max_f32_e32 v25, 0, v25
	global_store_dwordx4 v[96:97], v[32:35], off offset:256
	v_max_f32_e32 v28, 0, v28
	v_max_f32_e32 v29, 0, v29
	v_pk_mul_f32 v[32:33], v[24:25], v[24:25]
	v_max_f32_e32 v24, 0, v30
	v_max_f32_e32 v26, 0, v26
	v_max_f32_e32 v25, 0, v31
	v_max_f32_e32 v27, 0, v27
	v_pk_fma_f32 v[16:17], v[168:169], v[68:69], v[16:17] op_sel_hi:[0,1,1] neg_lo:[1,0,0] neg_hi:[1,0,0]
	v_pk_mul_f32 v[28:29], v[28:29], v[28:29]
	v_pk_mul_f32 v[30:31], v[24:25], v[24:25]
	v_pk_mul_f32 v[34:35], v[26:27], v[26:27]
	v_pk_fma_f32 v[20:21], v[168:169], v[72:73], v[20:21] op_sel_hi:[0,1,1] neg_lo:[1,0,0] neg_hi:[1,0,0]
	v_pk_fma_f32 v[22:23], v[168:169], v[74:75], v[22:23] op_sel_hi:[0,1,1] neg_lo:[1,0,0] neg_hi:[1,0,0]
	v_pk_fma_f32 v[18:19], v[168:169], v[70:71], v[18:19] op_sel_hi:[0,1,1] neg_lo:[1,0,0] neg_hi:[1,0,0]
	v_pk_fma_f32 v[16:17], v[190:191], v[16:17], v[64:65] op_sel_hi:[0,1,1]
	v_cvt_pk_bf16_f32 v24, v28, v29
	v_cvt_pk_bf16_f32 v25, v30, v31
	v_cvt_pk_bf16_f32 v26, v32, v33
	v_cvt_pk_bf16_f32 v27, v34, v35
	v_pk_fma_f32 v[22:23], v[190:191], v[22:23], v[78:79] op_sel_hi:[0,1,1]
	v_pk_fma_f32 v[20:21], v[190:191], v[20:21], v[76:77] op_sel_hi:[0,1,1]
	v_pk_fma_f32 v[18:19], v[190:191], v[18:19], v[66:67] op_sel_hi:[0,1,1]
	v_max_f32_e32 v16, 0, v16
	v_max_f32_e32 v17, 0, v17
	global_store_dwordx4 v[88:89], v[24:27], off offset:256
	v_max_f32_e32 v20, 0, v20
	v_max_f32_e32 v21, 0, v21
	v_pk_mul_f32 v[24:25], v[16:17], v[16:17]
	v_max_f32_e32 v16, 0, v22
	v_max_f32_e32 v18, 0, v18
	v_max_f32_e32 v17, 0, v23
	v_max_f32_e32 v19, 0, v19
	v_pk_fma_f32 v[8:9], v[178:179], v[68:69], v[8:9] op_sel_hi:[0,1,1] neg_lo:[1,0,0] neg_hi:[1,0,0]
	v_pk_mul_f32 v[20:21], v[20:21], v[20:21]
	v_pk_mul_f32 v[22:23], v[16:17], v[16:17]
	v_pk_mul_f32 v[26:27], v[18:19], v[18:19]
	v_pk_fma_f32 v[12:13], v[178:179], v[72:73], v[12:13] op_sel_hi:[0,1,1] neg_lo:[1,0,0] neg_hi:[1,0,0]
	v_pk_fma_f32 v[14:15], v[178:179], v[74:75], v[14:15] op_sel_hi:[0,1,1] neg_lo:[1,0,0] neg_hi:[1,0,0]
	v_pk_fma_f32 v[10:11], v[178:179], v[70:71], v[10:11] op_sel_hi:[0,1,1] neg_lo:[1,0,0] neg_hi:[1,0,0]
	v_pk_fma_f32 v[8:9], v[188:189], v[8:9], v[64:65] op_sel_hi:[0,1,1]
	v_cvt_pk_bf16_f32 v16, v20, v21
	v_cvt_pk_bf16_f32 v17, v22, v23
	v_cvt_pk_bf16_f32 v18, v24, v25
	v_cvt_pk_bf16_f32 v19, v26, v27
	v_pk_fma_f32 v[14:15], v[188:189], v[14:15], v[78:79] op_sel_hi:[0,1,1]
	v_pk_fma_f32 v[12:13], v[188:189], v[12:13], v[76:77] op_sel_hi:[0,1,1]
	v_pk_fma_f32 v[10:11], v[188:189], v[10:11], v[66:67] op_sel_hi:[0,1,1]
	v_max_f32_e32 v8, 0, v8
	v_max_f32_e32 v9, 0, v9
	global_store_dwordx4 v[80:81], v[16:19], off offset:256
	v_max_f32_e32 v12, 0, v12
	v_max_f32_e32 v13, 0, v13
	v_pk_mul_f32 v[16:17], v[8:9], v[8:9]
	v_max_f32_e32 v8, 0, v14
	v_max_f32_e32 v10, 0, v10
	v_max_f32_e32 v9, 0, v15
	v_max_f32_e32 v11, 0, v11
	v_pk_fma_f32 v[0:1], v[172:173], v[68:69], v[0:1] op_sel_hi:[0,1,1] neg_lo:[1,0,0] neg_hi:[1,0,0]
	v_pk_mul_f32 v[12:13], v[12:13], v[12:13]
	v_pk_mul_f32 v[14:15], v[8:9], v[8:9]
	v_pk_mul_f32 v[18:19], v[10:11], v[10:11]
	v_pk_fma_f32 v[4:5], v[172:173], v[72:73], v[4:5] op_sel_hi:[0,1,1] neg_lo:[1,0,0] neg_hi:[1,0,0]
	v_pk_fma_f32 v[6:7], v[172:173], v[74:75], v[6:7] op_sel_hi:[0,1,1] neg_lo:[1,0,0] neg_hi:[1,0,0]
	v_pk_fma_f32 v[2:3], v[172:173], v[70:71], v[2:3] op_sel_hi:[0,1,1] neg_lo:[1,0,0] neg_hi:[1,0,0]
	v_pk_fma_f32 v[0:1], v[180:181], v[0:1], v[64:65] op_sel_hi:[0,1,1]
	v_cvt_pk_bf16_f32 v8, v12, v13
	v_cvt_pk_bf16_f32 v9, v14, v15
	v_cvt_pk_bf16_f32 v10, v16, v17
	v_cvt_pk_bf16_f32 v11, v18, v19
	v_pk_fma_f32 v[6:7], v[180:181], v[6:7], v[78:79] op_sel_hi:[0,1,1]
	v_pk_fma_f32 v[4:5], v[180:181], v[4:5], v[76:77] op_sel_hi:[0,1,1]
	v_pk_fma_f32 v[2:3], v[180:181], v[2:3], v[66:67] op_sel_hi:[0,1,1]
	v_max_f32_e32 v0, 0, v0
	v_max_f32_e32 v1, 0, v1
	global_store_dwordx4 v[82:83], v[8:11], off offset:256
	v_max_f32_e32 v4, 0, v4
	v_max_f32_e32 v5, 0, v5
	v_pk_mul_f32 v[8:9], v[0:1], v[0:1]
	v_max_f32_e32 v0, 0, v6
	v_max_f32_e32 v2, 0, v2
	v_max_f32_e32 v1, 0, v7
	v_max_f32_e32 v3, 0, v3
	v_pk_mul_f32 v[4:5], v[4:5], v[4:5]
	v_pk_mul_f32 v[6:7], v[0:1], v[0:1]
	v_pk_mul_f32 v[10:11], v[2:3], v[2:3]
	v_cvt_pk_bf16_f32 v0, v4, v5
	v_cvt_pk_bf16_f32 v1, v6, v7
	v_cvt_pk_bf16_f32 v2, v8, v9
	v_cvt_pk_bf16_f32 v3, v10, v11
	global_store_dwordx4 v[84:85], v[0:3], off offset:256
	s_cbranch_vccnz .LBB0_1376
	s_andn2_b64 vcc, exec, s[20:21]
	s_cbranch_vccnz .LBB0_1375
	s_barrier
	s_branch .LBB0_1375
